# speedup vs baseline: 1.0024x; 1.0024x over previous
; #define PG8_STAGE(bufoff, gbase, voff) do { _Pragma("unroll") for (int _i = 0; _i < 2; ++_i) \
;         __builtin_amdgcn_global_load_lds((const unsigned*)((const char*)(gbase) + (voff)[_i]), (PG8_LAS unsigned*)(lds + (bufoff) + ldsw + _i * 8192), 16, 0, 0); } while (0)
; #define PG8_LDA(dst, b, h) do { _Pragma("unroll") for (int m = 0; m < 4; ++m) _Pragma("unroll") for (int k = 0; k < 2; ++k) dst[m][k] = *(const PG8_LAS bf16x8*)(lds + PG8_SA(b, h) + aoff + m * 2048 + k * 1024); } while (0)
; #define PG8_LDB(dst, b, h) do { _Pragma("unroll") for (int n = 0; n < 2; ++n) _Pragma("unroll") for (int k = 0; k < 2; ++k) dst[n][k] = *(const PG8_LAS bf16x8*)(lds + PG8_SB(b, h) + boff + n * 2048 + k * 1024); } while (0)
; #define PG8_SCHED __builtin_amdgcn_sched_barrier(0)
; template <class Epi, class Sched, bool ALIGN_EPI = false, bool SP2 = false>
; __device__ __forceinline__ void gemm_phase(PG8_LAS unsigned char* lds, const Gemm g, const Sched& S, const Epi& E) {
;     ...
;         const bool has_next = S.next(ui + 1, nxt);
;         const char* nA = has_next ? (const char*)g.A + (size_t)nxt.pm * tstep : cA; const char* nB = has_next ? (const char*)g.Bt + (size_t)nxt.pn * tstep : cB;
;         for (int t = 0; t < nt; t += 2) {
;             if constexpr (Epi::MID_HOOK) { if (t == Epi::MID_T) E.mid(acc, cur, wr, wc, fr, fq); }
;             const bool last = (t == nt - 2);
;             const char* a1 = cA + (size_t)(t + 1) * kstep;
;             const char* a2 = last ? nA : cA + (size_t)(t + 2) * kstep; const char* b2 = last ? nB : cB + (size_t)(t + 2) * kstep;
;             const char* a3 = a2 + kstep; const char* b3 = b2 + kstep;
;             if (last && has_next) S.a_ready(nxt);
;             if constexpr (SP2) {
;             PG8_LDB(B0, 0, 0); PG8_LDB(B1, 0, 1); PG8_SCHED; PG8_LDA(At, 0, 0); PG8_STAGE(PG8_SA(1, 1), a1 + hstep, voffA);
.LBB0_122:
	v_add_u32_e32 v152, 0x10000, v178
	v_add_u32_e32 v168, 0x14000, v178
	ds_read_b128 v[128:131], v152
	ds_read_b128 v[132:135], v152 offset:1024
	ds_read_b128 v[148:151], v152 offset:2048
	ds_read_b128 v[152:155], v152 offset:3072
	ds_read_b128 v[156:159], v168
	ds_read_b128 v[160:163], v168 offset:1024
	ds_read_b128 v[164:167], v168 offset:2048
	ds_read_b128 v[168:171], v168 offset:3072
	ds_read_b128 v[172:175], v179
	ds_read_b128 v[180:183], v179 offset:1024
	ds_read_b128 v[184:187], v179 offset:2048
	ds_read_b128 v[188:191], v179 offset:3072
	ds_read_b128 v[206:209], v179 offset:4096
	ds_read_b128 v[210:213], v179 offset:5120
	ds_read_b128 v[214:217], v179 offset:6144
	ds_read_b128 v[218:221], v179 offset:7168
	s_add_i32 s84, s2, 1
	s_mov_b64 s[14:15], -1
	s_andn2_b64 vcc, exec, s[6:7]
	s_mov_b32 s11, s84
	s_cbranch_vccnz .LBB0_125
	s_cmp_lt_u32 s2, 12
	s_mov_b64 s[14:15], 0
	s_cbranch_scc0 .LBB0_125
	v_readlane_b32 s2, v254, 39
	s_add_i32 s2, s84, s2
	s_cmp_lt_u32 s2, 13
	s_cselect_b32 s11, 0, -13
	s_add_i32 s11, s11, s2
	s_mov_b64 s[14:15], -1

; #define PG8_STAGE(bufoff, gbase, voff) do { _Pragma("unroll") for (int _i = 0; _i < 2; ++_i) \
;         __builtin_amdgcn_global_load_lds((const unsigned*)((const char*)(gbase) + (voff)[_i]), (PG8_LAS unsigned*)(lds + (bufoff) + ldsw + _i * 8192), 16, 0, 0); } while (0)
; #define PG8_LDA(dst, b, h) do { _Pragma("unroll") for (int m = 0; m < 4; ++m) _Pragma("unroll") for (int k = 0; k < 2; ++k) dst[m][k] = *(const PG8_LAS bf16x8*)(lds + PG8_SA(b, h) + aoff + m * 2048 + k * 1024); } while (0)
; #define PG8_LDB(dst, b, h) do { _Pragma("unroll") for (int n = 0; n < 2; ++n) _Pragma("unroll") for (int k = 0; k < 2; ++k) dst[n][k] = *(const PG8_LAS bf16x8*)(lds + PG8_SB(b, h) + boff + n * 2048 + k * 1024); } while (0)
; #define PG8_WAIT_V(n) asm volatile("s_waitcnt vmcnt(" #n ")" ::: "memory")
; #define PG8_WAIT_L(n) asm volatile("s_waitcnt lgkmcnt(" #n ")" ::: "memory")
; #define PG8_BAR __builtin_amdgcn_s_barrier()
; template <class Epi, class Sched, bool ALIGN_EPI = false, bool SP2 = false>
; __device__ __forceinline__ void gemm_phase(PG8_LAS unsigned char* lds, const Gemm g, const Sched& S, const Epi& E) {
;     ...
;         const bool has_next = S.next(ui + 1, nxt);
;         const char* nA = has_next ? (const char*)g.A + (size_t)nxt.pm * tstep : cA; const char* nB = has_next ? (const char*)g.Bt + (size_t)nxt.pn * tstep : cB;
;         for (int t = 0; t < nt; t += 2) {
;             if constexpr (Epi::MID_HOOK) { if (t == Epi::MID_T) E.mid(acc, cur, wr, wc, fr, fq); }
;             const bool last = (t == nt - 2);
;             const char* a1 = cA + (size_t)(t + 1) * kstep;
;             const char* a2 = last ? nA : cA + (size_t)(t + 2) * kstep; const char* b2 = last ? nB : cB + (size_t)(t + 2) * kstep;
;             const char* a3 = a2 + kstep; const char* b3 = b2 + kstep;
;             if (last && has_next) S.a_ready(nxt);
;             if constexpr (SP2) {
;             PG8_LDB(B0, 0, 0); PG8_LDB(B1, 0, 1); PG8_SCHED; PG8_LDA(At, 0, 0); PG8_STAGE(PG8_SA(1, 1), a1 + hstep, voffA);
;             PG8_WAIT_V(8); PG8_WAIT_L(0); PG8_BAR; PG8_MMA(0, 0, At, B0); PG8_MMA(0, 1, At, B1); PG8_BAR; PG8_SCHED;
;             PG8_LDA(At, 0, 1); PG8_STAGE(PG8_SB(0, 0), b2, voffB); PG8_STAGE(PG8_SB(0, 1), b2 + hstep, voffB); PG8_STAGE(PG8_SA(0, 0), a2, voffA);
;             PG8_WAIT_V(8); PG8_WAIT_L(0); PG8_BAR; PG8_MMA(1, 0, At, B0); PG8_MMA(1, 1, At, B1); PG8_BAR; PG8_SCHED;
.LBB0_128:
	s_ashr_i32 s67, s66, 31
	s_lshl_b64 s[14:15], s[66:67], 20
	s_add_u32 s70, s37, s14
	s_addc_u32 s71, s38, s15
	s_and_b64 s[14:15], s[68:69], exec
	s_cselect_b32 s2, s71, s1
	s_cselect_b32 s11, s70, s0
	s_ashr_i32 s65, s64, 31
	s_lshl_b64 s[14:15], s[64:65], 20
	s_add_u32 s72, s31, s14
	s_addc_u32 s73, s36, s15
	s_and_b64 s[14:15], s[68:69], exec
	s_cselect_b32 s18, s73, s13
	s_cselect_b32 s19, s72, s12
	s_add_u32 s0, s0, 0x80080
	s_addc_u32 s1, s1, 0
	s_add_u32 s34, s12, 0x100
	s_addc_u32 s41, s13, 0
	s_mov_b32 s42, -2
	v_lshl_add_u64 v[194:195], s[0:1], 0, v[144:145]
	s_add_i32 m0, s74, 0xc000
	global_load_lds_dwordx4 v[194:195], off
	s_add_i32 m0, s74, 0xe000
	v_lshl_add_u64 v[194:195], s[0:1], 0, v[146:147]
	global_load_lds_dwordx4 v[194:195], off
	s_add_u32 s12, s0, 0xfff80080
	s_addc_u32 s13, s1, -1
	s_add_i32 s43, 0, 0x10000
	s_cmp_eq_u32 s42, 28
	s_cselect_b32 s15, s2, s13
	s_cselect_b32 s14, s11, s12
	s_cselect_b32 s13, s18, s41
	s_cselect_b32 s12, s19, s34
	s_add_i32 s65, 0, 0x14000
	s_waitcnt vmcnt(8)
	s_waitcnt lgkmcnt(0)
	s_barrier
	s_setprio 1
	s_waitcnt lgkmcnt(0)
	v_mfma_f32_16x16x32_bf16 v[124:127], v[128:131], v[172:175], 0
	v_mfma_f32_16x16x32_bf16 v[120:123], v[148:151], v[172:175], 0
	v_mfma_f32_16x16x32_bf16 v[108:111], v[128:131], v[184:187], 0
	v_mfma_f32_16x16x32_bf16 v[104:107], v[148:151], v[184:187], 0
	v_mfma_f32_16x16x32_bf16 v[92:95], v[128:131], v[206:209], 0
	v_mfma_f32_16x16x32_bf16 v[88:91], v[148:151], v[206:209], 0
	v_mfma_f32_16x16x32_bf16 v[76:79], v[128:131], v[214:217], 0
	v_mfma_f32_16x16x32_bf16 v[72:75], v[148:151], v[214:217], 0
	v_mfma_f32_16x16x32_bf16 v[124:127], v[132:135], v[180:183], v[124:127]
	v_mfma_f32_16x16x32_bf16 v[120:123], v[152:155], v[180:183], v[120:123]
	v_mfma_f32_16x16x32_bf16 v[108:111], v[132:135], v[188:191], v[108:111]
	v_mfma_f32_16x16x32_bf16 v[104:107], v[152:155], v[188:191], v[104:107]
	v_mfma_f32_16x16x32_bf16 v[92:95], v[132:135], v[210:213], v[92:95]
	v_mfma_f32_16x16x32_bf16 v[88:91], v[152:155], v[210:213], v[88:91]
	v_mfma_f32_16x16x32_bf16 v[76:79], v[132:135], v[218:221], v[76:79]
	v_mfma_f32_16x16x32_bf16 v[72:75], v[152:155], v[218:221], v[72:75]
	s_setprio 0
	s_setprio 1
	v_mfma_f32_16x16x32_bf16 v[116:119], v[156:159], v[172:175], 0
	v_mfma_f32_16x16x32_bf16 v[112:115], v[164:167], v[172:175], 0
	v_mfma_f32_16x16x32_bf16 v[100:103], v[156:159], v[184:187], 0
	v_mfma_f32_16x16x32_bf16 v[96:99], v[164:167], v[184:187], 0
	v_mfma_f32_16x16x32_bf16 v[84:87], v[156:159], v[206:209], 0
	v_mfma_f32_16x16x32_bf16 v[80:83], v[164:167], v[206:209], 0
	v_mfma_f32_16x16x32_bf16 v[68:71], v[156:159], v[214:217], 0
	v_mfma_f32_16x16x32_bf16 v[64:67], v[164:167], v[214:217], 0
	v_mfma_f32_16x16x32_bf16 v[116:119], v[160:163], v[180:183], v[116:119]
	v_mfma_f32_16x16x32_bf16 v[112:115], v[168:171], v[180:183], v[112:115]
	v_mfma_f32_16x16x32_bf16 v[100:103], v[160:163], v[188:191], v[100:103]
	v_mfma_f32_16x16x32_bf16 v[96:99], v[168:171], v[188:191], v[96:99]
	v_mfma_f32_16x16x32_bf16 v[84:87], v[160:163], v[210:213], v[84:87]
	v_mfma_f32_16x16x32_bf16 v[80:83], v[168:171], v[210:213], v[80:83]
	v_mfma_f32_16x16x32_bf16 v[68:71], v[160:163], v[218:221], v[68:71]
	v_mfma_f32_16x16x32_bf16 v[64:67], v[168:171], v[218:221], v[64:67]
	s_setprio 0
	s_barrier
	s_add_i32 s43, s43, s39
	v_lshl_add_u64 v[194:195], s[12:13], 0, v[138:139]
	s_mov_b32 m0, s43
	ds_read_b128 v[172:175], v179 offset:16384
	ds_read_b128 v[180:183], v179 offset:17408
	ds_read_b128 v[184:187], v179 offset:18432
	ds_read_b128 v[188:191], v179 offset:19456
	ds_read_b128 v[206:209], v179 offset:20480
	ds_read_b128 v[210:213], v179 offset:21504
	ds_read_b128 v[214:217], v179 offset:22528
	ds_read_b128 v[218:221], v179 offset:23552
	global_load_lds_dwordx4 v[194:195], off
	s_add_i32 m0, s43, 0x2000
	s_add_u32 s86, s12, 0x80000
	v_lshl_add_u64 v[196:197], s[12:13], 0, v[142:143]
	s_addc_u32 s87, s13, 0
	s_add_i32 s43, s65, s39
	global_load_lds_dwordx4 v[196:197], off
	v_lshl_add_u64 v[202:203], s[86:87], 0, v[138:139]
	s_mov_b32 m0, s43
	v_lshl_add_u64 v[204:205], s[14:15], 0, v[140:141]
	global_load_lds_dwordx4 v[202:203], off
	s_add_i32 m0, s43, 0x2000
	v_lshl_add_u64 v[202:203], s[86:87], 0, v[142:143]
	global_load_lds_dwordx4 v[202:203], off
	s_mov_b32 m0, s74
	v_lshl_add_u64 v[202:203], s[14:15], 0, v[136:137]
	global_load_lds_dwordx4 v[202:203], off
	s_mov_b32 m0, s75
	s_nop 0
	global_load_lds_dwordx4 v[204:205], off
	s_waitcnt vmcnt(8)
	s_waitcnt lgkmcnt(0)
	s_barrier
	s_setprio 1
	s_waitcnt lgkmcnt(0)
	v_mfma_f32_16x16x32_bf16 v[60:63], v[128:131], v[172:175], 0
	v_mfma_f32_16x16x32_bf16 v[56:59], v[148:151], v[172:175], 0
	v_mfma_f32_16x16x32_bf16 v[44:47], v[128:131], v[184:187], 0
	v_mfma_f32_16x16x32_bf16 v[40:43], v[148:151], v[184:187], 0
	v_mfma_f32_16x16x32_bf16 v[28:31], v[128:131], v[206:209], 0
	v_mfma_f32_16x16x32_bf16 v[24:27], v[148:151], v[206:209], 0
	v_mfma_f32_16x16x32_bf16 v[12:15], v[128:131], v[214:217], 0
	v_mfma_f32_16x16x32_bf16 v[8:11], v[148:151], v[214:217], 0
	v_mfma_f32_16x16x32_bf16 v[60:63], v[132:135], v[180:183], v[60:63]
	v_mfma_f32_16x16x32_bf16 v[56:59], v[152:155], v[180:183], v[56:59]
	v_mfma_f32_16x16x32_bf16 v[44:47], v[132:135], v[188:191], v[44:47]
	v_mfma_f32_16x16x32_bf16 v[40:43], v[152:155], v[188:191], v[40:43]
	v_mfma_f32_16x16x32_bf16 v[28:31], v[132:135], v[210:213], v[28:31]
	v_mfma_f32_16x16x32_bf16 v[24:27], v[152:155], v[210:213], v[24:27]
	v_mfma_f32_16x16x32_bf16 v[12:15], v[132:135], v[218:221], v[12:15]
	v_mfma_f32_16x16x32_bf16 v[8:11], v[152:155], v[218:221], v[8:11]
	s_setprio 0
	s_setprio 1
	v_mfma_f32_16x16x32_bf16 v[52:55], v[156:159], v[172:175], 0
	v_mfma_f32_16x16x32_bf16 v[48:51], v[164:167], v[172:175], 0
	v_mfma_f32_16x16x32_bf16 v[36:39], v[156:159], v[184:187], 0
	v_mfma_f32_16x16x32_bf16 v[32:35], v[164:167], v[184:187], 0
	v_mfma_f32_16x16x32_bf16 v[20:23], v[156:159], v[206:209], 0
	v_mfma_f32_16x16x32_bf16 v[16:19], v[164:167], v[206:209], 0
	v_mfma_f32_16x16x32_bf16 v[4:7], v[156:159], v[214:217], 0
	v_mfma_f32_16x16x32_bf16 v[0:3], v[164:167], v[214:217], 0
	v_mfma_f32_16x16x32_bf16 v[52:55], v[160:163], v[180:183], v[52:55]
	v_mfma_f32_16x16x32_bf16 v[48:51], v[168:171], v[180:183], v[48:51]
	v_mfma_f32_16x16x32_bf16 v[36:39], v[160:163], v[188:191], v[36:39]
	v_mfma_f32_16x16x32_bf16 v[32:35], v[168:171], v[188:191], v[32:35]
	v_mfma_f32_16x16x32_bf16 v[20:23], v[160:163], v[210:213], v[20:23]
	v_mfma_f32_16x16x32_bf16 v[16:19], v[168:171], v[210:213], v[16:19]
	v_mfma_f32_16x16x32_bf16 v[4:7], v[160:163], v[218:221], v[4:7]
	v_mfma_f32_16x16x32_bf16 v[0:3], v[168:171], v[218:221], v[0:3]
	s_setprio 0
	s_barrier
; #define PG8_STAGE(bufoff, gbase, voff) do { _Pragma("unroll") for (int _i = 0; _i < 2; ++_i) \
;         __builtin_amdgcn_global_load_lds((const unsigned*)((const char*)(gbase) + (voff)[_i]), (PG8_LAS unsigned*)(lds + (bufoff) + ldsw + _i * 8192), 16, 0, 0); } while (0)
; #define PG8_LDA(dst, b, h) do { _Pragma("unroll") for (int m = 0; m < 4; ++m) _Pragma("unroll") for (int k = 0; k < 2; ++k) dst[m][k] = *(const PG8_LAS bf16x8*)(lds + PG8_SA(b, h) + aoff + m * 2048 + k * 1024); } while (0)
; #define PG8_LDB(dst, b, h) do { _Pragma("unroll") for (int n = 0; n < 2; ++n) _Pragma("unroll") for (int k = 0; k < 2; ++k) dst[n][k] = *(const PG8_LAS bf16x8*)(lds + PG8_SB(b, h) + boff + n * 2048 + k * 1024); } while (0)
; #define PG8_MMA(ai, bj, At, Bt) do { __builtin_amdgcn_s_setprio(1); _Pragma("unroll") for (int m = 0; m < 4; ++m) _Pragma("unroll") for (int n = 0; n < 2; ++n) _Pragma("unroll") for (int k = 0; k < 2; ++k) \
;         acc[ai][bj][m][n] = __builtin_amdgcn_mfma_f32_16x16x32_bf16(Bt[n][k], At[m][k], acc[ai][bj][m][n], 0, 0, 0); __builtin_amdgcn_s_setprio(0); } while (0)
; #define PG8_WAIT_V(n) asm volatile("s_waitcnt vmcnt(" #n ")" ::: "memory")
; #define PG8_WAIT_L(n) asm volatile("s_waitcnt lgkmcnt(" #n ")" ::: "memory")
; #define PG8_BAR __builtin_amdgcn_s_barrier()
; #define PG8_SCHED __builtin_amdgcn_sched_barrier(0)
; template <class Epi, class Sched, bool ALIGN_EPI = false, bool SP2 = false>
; __device__ __forceinline__ void gemm_phase(PG8_LAS unsigned char* lds, const Gemm g, const Sched& S, const Epi& E) {
;     ...
;             PG8_LDB(B0, 1, 0); PG8_LDB(B1, 1, 1); PG8_SCHED; PG8_LDA(At, 1, 0); PG8_STAGE(PG8_SA(0, 1), a2 + hstep, voffA);
;             PG8_WAIT_V(8); PG8_WAIT_L(0); PG8_BAR; PG8_MMA(0, 0, At, B0); PG8_MMA(0, 1, At, B1); PG8_BAR; PG8_SCHED;
	s_add_i32 s43, 0, 0x18000
	s_add_i32 s65, 0, 0x1c000
	v_add_u32_e32 v152, 0x18000, v178
	v_add_u32_e32 v168, 0x1c000, v178
	ds_read_b128 v[128:131], v152
	ds_read_b128 v[132:135], v152 offset:1024
	ds_read_b128 v[148:151], v152 offset:2048
	ds_read_b128 v[152:155], v152 offset:3072
	ds_read_b128 v[156:159], v168
	ds_read_b128 v[160:163], v168 offset:1024
	ds_read_b128 v[164:167], v168 offset:2048
	ds_read_b128 v[168:171], v168 offset:3072
	s_add_u32 s14, s14, 0x80000
	s_addc_u32 s15, s15, 0
	s_mov_b32 m0, s76
	v_lshl_add_u64 v[232:233], s[14:15], 0, v[136:137]
	ds_read_b128 v[172:175], v179 offset:32768
	ds_read_b128 v[180:183], v179 offset:33792
	ds_read_b128 v[184:187], v179 offset:34816
	ds_read_b128 v[188:191], v179 offset:35840
	ds_read_b128 v[206:209], v179 offset:36864
	ds_read_b128 v[210:213], v179 offset:37888
	ds_read_b128 v[214:217], v179 offset:38912
	ds_read_b128 v[218:221], v179 offset:39936
	global_load_lds_dwordx4 v[232:233], off
	s_mov_b32 m0, s77
	v_lshl_add_u64 v[232:233], s[14:15], 0, v[140:141]
	global_load_lds_dwordx4 v[232:233], off
	s_waitcnt vmcnt(8)
	s_waitcnt lgkmcnt(0)
	s_barrier
	s_setprio 1
	s_waitcnt lgkmcnt(0)
	v_mfma_f32_16x16x32_bf16 v[124:127], v[128:131], v[172:175], v[124:127]
	v_mfma_f32_16x16x32_bf16 v[120:123], v[148:151], v[172:175], v[120:123]
	v_mfma_f32_16x16x32_bf16 v[108:111], v[128:131], v[184:187], v[108:111]
	v_mfma_f32_16x16x32_bf16 v[104:107], v[148:151], v[184:187], v[104:107]
	v_mfma_f32_16x16x32_bf16 v[92:95], v[128:131], v[206:209], v[92:95]
	v_mfma_f32_16x16x32_bf16 v[88:91], v[148:151], v[206:209], v[88:91]
	v_mfma_f32_16x16x32_bf16 v[76:79], v[128:131], v[214:217], v[76:79]
	v_mfma_f32_16x16x32_bf16 v[72:75], v[148:151], v[214:217], v[72:75]
	v_mfma_f32_16x16x32_bf16 v[124:127], v[132:135], v[180:183], v[124:127]
	v_mfma_f32_16x16x32_bf16 v[120:123], v[152:155], v[180:183], v[120:123]
	v_mfma_f32_16x16x32_bf16 v[108:111], v[132:135], v[188:191], v[108:111]
	v_mfma_f32_16x16x32_bf16 v[104:107], v[152:155], v[188:191], v[104:107]
	v_mfma_f32_16x16x32_bf16 v[92:95], v[132:135], v[210:213], v[92:95]
	v_mfma_f32_16x16x32_bf16 v[88:91], v[152:155], v[210:213], v[88:91]
	v_mfma_f32_16x16x32_bf16 v[76:79], v[132:135], v[218:221], v[76:79]
	v_mfma_f32_16x16x32_bf16 v[72:75], v[152:155], v[218:221], v[72:75]
	s_setprio 0
	s_setprio 1
	v_mfma_f32_16x16x32_bf16 v[116:119], v[156:159], v[172:175], v[116:119]
	v_mfma_f32_16x16x32_bf16 v[112:115], v[164:167], v[172:175], v[112:115]
	v_mfma_f32_16x16x32_bf16 v[100:103], v[156:159], v[184:187], v[100:103]
	v_mfma_f32_16x16x32_bf16 v[96:99], v[164:167], v[184:187], v[96:99]
	v_mfma_f32_16x16x32_bf16 v[84:87], v[156:159], v[206:209], v[84:87]
	v_mfma_f32_16x16x32_bf16 v[80:83], v[164:167], v[206:209], v[80:83]
	v_mfma_f32_16x16x32_bf16 v[68:71], v[156:159], v[214:217], v[68:71]
	v_mfma_f32_16x16x32_bf16 v[64:67], v[164:167], v[214:217], v[64:67]
	v_mfma_f32_16x16x32_bf16 v[116:119], v[160:163], v[180:183], v[116:119]
	v_mfma_f32_16x16x32_bf16 v[112:115], v[168:171], v[180:183], v[112:115]
	v_mfma_f32_16x16x32_bf16 v[100:103], v[160:163], v[188:191], v[100:103]
	v_mfma_f32_16x16x32_bf16 v[96:99], v[168:171], v[188:191], v[96:99]
	v_mfma_f32_16x16x32_bf16 v[84:87], v[160:163], v[210:213], v[84:87]
	v_mfma_f32_16x16x32_bf16 v[80:83], v[168:171], v[210:213], v[80:83]
	v_mfma_f32_16x16x32_bf16 v[68:71], v[160:163], v[218:221], v[68:71]
	v_mfma_f32_16x16x32_bf16 v[64:67], v[168:171], v[218:221], v[64:67]
	s_setprio 0
	s_barrier
; #define PG8_STAGE(bufoff, gbase, voff) do { _Pragma("unroll") for (int _i = 0; _i < 2; ++_i) \
;         __builtin_amdgcn_global_load_lds((const unsigned*)((const char*)(gbase) + (voff)[_i]), (PG8_LAS unsigned*)(lds + (bufoff) + ldsw + _i * 8192), 16, 0, 0); } while (0)
; #define PG8_LDA(dst, b, h) do { _Pragma("unroll") for (int m = 0; m < 4; ++m) _Pragma("unroll") for (int k = 0; k < 2; ++k) dst[m][k] = *(const PG8_LAS bf16x8*)(lds + PG8_SA(b, h) + aoff + m * 2048 + k * 1024); } while (0)
; #define PG8_MMA(ai, bj, At, Bt) do { __builtin_amdgcn_s_setprio(1); _Pragma("unroll") for (int m = 0; m < 4; ++m) _Pragma("unroll") for (int n = 0; n < 2; ++n) _Pragma("unroll") for (int k = 0; k < 2; ++k) \
;         acc[ai][bj][m][n] = __builtin_amdgcn_mfma_f32_16x16x32_bf16(Bt[n][k], At[m][k], acc[ai][bj][m][n], 0, 0, 0); __builtin_amdgcn_s_setprio(0); } while (0)
; #define PG8_WAIT_V(n) asm volatile("s_waitcnt vmcnt(" #n ")" ::: "memory")
; #define PG8_WAIT_L(n) asm volatile("s_waitcnt lgkmcnt(" #n ")" ::: "memory")
; #define PG8_BAR __builtin_amdgcn_s_barrier()
; #define PG8_SCHED __builtin_amdgcn_sched_barrier(0)
; template <class Epi, class Sched, bool ALIGN_EPI = false, bool SP2 = false>
; __device__ __forceinline__ void gemm_phase(PG8_LAS unsigned char* lds, const Gemm g, const Sched& S, const Epi& E) {
;     ...
;             PG8_LDA(At, 1, 1); PG8_STAGE(PG8_SB(1, 0), b3, voffB); PG8_STAGE(PG8_SB(1, 1), b3 + hstep, voffB); PG8_STAGE(PG8_SA(1, 0), a3, voffA);
;             PG8_WAIT_V(8); PG8_WAIT_L(0); PG8_BAR; PG8_MMA(1, 0, At, B0); PG8_MMA(1, 1, At, B1); PG8_BAR; PG8_SCHED;
	s_add_i32 s14, s43, s39
	v_lshl_add_u64 v[194:195], v[194:195], 0, s[16:17]
	s_mov_b32 m0, s14
	ds_read_b128 v[172:175], v179 offset:49152
	ds_read_b128 v[180:183], v179 offset:50176
	ds_read_b128 v[184:187], v179 offset:51200
	ds_read_b128 v[188:191], v179 offset:52224
	ds_read_b128 v[206:209], v179 offset:53248
	ds_read_b128 v[210:213], v179 offset:54272
	ds_read_b128 v[214:217], v179 offset:55296
	ds_read_b128 v[218:221], v179 offset:56320
	global_load_lds_dwordx4 v[194:195], off
	s_add_i32 m0, s14, 0x2000
	s_add_u32 s12, s12, 0x80080
	v_lshl_add_u64 v[194:195], v[196:197], 0, s[16:17]
	s_addc_u32 s13, s13, 0
	s_add_i32 s14, s65, s39
	global_load_lds_dwordx4 v[194:195], off
	s_mov_b32 m0, s14
	v_lshl_add_u64 v[194:195], s[12:13], 0, v[138:139]
	global_load_lds_dwordx4 v[194:195], off
	s_add_i32 m0, s14, 0x2000
	v_lshl_add_u64 v[194:195], s[12:13], 0, v[142:143]
	global_load_lds_dwordx4 v[194:195], off
	s_mov_b32 m0, s80
	v_lshl_add_u64 v[194:195], v[202:203], 0, s[16:17]
	global_load_lds_dwordx4 v[194:195], off
	s_mov_b32 m0, s81
	v_lshl_add_u64 v[194:195], v[204:205], 0, s[16:17]
	global_load_lds_dwordx4 v[194:195], off
	s_waitcnt vmcnt(8)
	s_waitcnt lgkmcnt(0)
	s_barrier
	s_setprio 1
	s_waitcnt lgkmcnt(0)
	v_mfma_f32_16x16x32_bf16 v[60:63], v[128:131], v[172:175], v[60:63]
	v_mfma_f32_16x16x32_bf16 v[56:59], v[148:151], v[172:175], v[56:59]
	v_mfma_f32_16x16x32_bf16 v[44:47], v[128:131], v[184:187], v[44:47]
	v_mfma_f32_16x16x32_bf16 v[40:43], v[148:151], v[184:187], v[40:43]
	v_mfma_f32_16x16x32_bf16 v[28:31], v[128:131], v[206:209], v[28:31]
	v_mfma_f32_16x16x32_bf16 v[24:27], v[148:151], v[206:209], v[24:27]
	v_mfma_f32_16x16x32_bf16 v[12:15], v[128:131], v[214:217], v[12:15]
	v_mfma_f32_16x16x32_bf16 v[8:11], v[148:151], v[214:217], v[8:11]
	v_mfma_f32_16x16x32_bf16 v[60:63], v[132:135], v[180:183], v[60:63]
	v_mfma_f32_16x16x32_bf16 v[56:59], v[152:155], v[180:183], v[56:59]
	v_mfma_f32_16x16x32_bf16 v[44:47], v[132:135], v[188:191], v[44:47]
	v_mfma_f32_16x16x32_bf16 v[40:43], v[152:155], v[188:191], v[40:43]
	v_mfma_f32_16x16x32_bf16 v[28:31], v[132:135], v[210:213], v[28:31]
	v_mfma_f32_16x16x32_bf16 v[24:27], v[152:155], v[210:213], v[24:27]
	v_mfma_f32_16x16x32_bf16 v[12:15], v[132:135], v[218:221], v[12:15]
	v_mfma_f32_16x16x32_bf16 v[8:11], v[152:155], v[218:221], v[8:11]
	s_setprio 0
	s_setprio 1
	v_mfma_f32_16x16x32_bf16 v[52:55], v[156:159], v[172:175], v[52:55]
	v_mfma_f32_16x16x32_bf16 v[48:51], v[164:167], v[172:175], v[48:51]
	v_mfma_f32_16x16x32_bf16 v[36:39], v[156:159], v[184:187], v[36:39]
	v_mfma_f32_16x16x32_bf16 v[32:35], v[164:167], v[184:187], v[32:35]
	v_mfma_f32_16x16x32_bf16 v[20:23], v[156:159], v[206:209], v[20:23]
	v_mfma_f32_16x16x32_bf16 v[16:19], v[164:167], v[206:209], v[16:19]
	v_mfma_f32_16x16x32_bf16 v[4:7], v[156:159], v[214:217], v[4:7]
	v_mfma_f32_16x16x32_bf16 v[0:3], v[164:167], v[214:217], v[0:3]
	v_mfma_f32_16x16x32_bf16 v[52:55], v[160:163], v[180:183], v[52:55]
	v_mfma_f32_16x16x32_bf16 v[48:51], v[168:171], v[180:183], v[48:51]
	v_mfma_f32_16x16x32_bf16 v[36:39], v[160:163], v[188:191], v[36:39]
	v_mfma_f32_16x16x32_bf16 v[32:35], v[168:171], v[188:191], v[32:35]
	v_mfma_f32_16x16x32_bf16 v[20:23], v[160:163], v[210:213], v[20:23]
	v_mfma_f32_16x16x32_bf16 v[16:19], v[168:171], v[210:213], v[16:19]
	v_mfma_f32_16x16x32_bf16 v[4:7], v[160:163], v[218:221], v[4:7]
	v_mfma_f32_16x16x32_bf16 v[0:3], v[168:171], v[218:221], v[0:3]
	s_setprio 0
	s_barrier
	s_add_i32 s42, s42, 2
	s_add_u32 s0, s0, 0x100
	s_addc_u32 s1, s1, 0
	s_add_u32 s34, s34, 0x100
	s_addc_u32 s41, s41, 0
	s_cmp_gt_u32 s42, 29
	s_branch .LBB0_129

; #define PG8_STAGE(bufoff, gbase, voff) do { _Pragma("unroll") for (int _i = 0; _i < 2; ++_i) \
;         __builtin_amdgcn_global_load_lds((const unsigned*)((const char*)(gbase) + (voff)[_i]), (PG8_LAS unsigned*)(lds + (bufoff) + ldsw + _i * 8192), 16, 0, 0); } while (0)
; #define PG8_LDA(dst, b, h) do { _Pragma("unroll") for (int m = 0; m < 4; ++m) _Pragma("unroll") for (int k = 0; k < 2; ++k) dst[m][k] = *(const PG8_LAS bf16x8*)(lds + PG8_SA(b, h) + aoff + m * 2048 + k * 1024); } while (0)
; #define PG8_LDB(dst, b, h) do { _Pragma("unroll") for (int n = 0; n < 2; ++n) _Pragma("unroll") for (int k = 0; k < 2; ++k) dst[n][k] = *(const PG8_LAS bf16x8*)(lds + PG8_SB(b, h) + boff + n * 2048 + k * 1024); } while (0)
; #define PG8_SCHED __builtin_amdgcn_sched_barrier(0)
; template <class Epi, class Sched, bool ALIGN_EPI = false, bool SP2 = false>
; __device__ __forceinline__ void gemm_phase(PG8_LAS unsigned char* lds, const Gemm g, const Sched& S, const Epi& E) {
;     ...
;         const bool has_next = S.next(ui + 1, nxt);
;         const char* nA = has_next ? (const char*)g.A + (size_t)nxt.pm * tstep : cA; const char* nB = has_next ? (const char*)g.Bt + (size_t)nxt.pn * tstep : cB;
;         for (int t = 0; t < nt; t += 2) {
;             if constexpr (Epi::MID_HOOK) { if (t == Epi::MID_T) E.mid(acc, cur, wr, wc, fr, fq); }
;             const bool last = (t == nt - 2);
;             const char* a1 = cA + (size_t)(t + 1) * kstep;
;             const char* a2 = last ? nA : cA + (size_t)(t + 2) * kstep; const char* b2 = last ? nB : cB + (size_t)(t + 2) * kstep;
;             const char* a3 = a2 + kstep; const char* b3 = b2 + kstep;
;             if (last && has_next) S.a_ready(nxt);
;             if constexpr (SP2) {
;             PG8_LDB(B0, 0, 0); PG8_LDB(B1, 0, 1); PG8_SCHED; PG8_LDA(At, 0, 0); PG8_STAGE(PG8_SA(1, 1), a1 + hstep, voffA);
.LBB0_628:
	v_add_u32_e32 v140, 0x10000, v172
	v_add_u32_e32 v168, 0x14000, v172
	ds_read_b128 v[128:131], v140
	ds_read_b128 v[132:135], v140 offset:1024
	ds_read_b128 v[136:139], v140 offset:2048
	ds_read_b128 v[140:143], v140 offset:3072
	ds_read_b128 v[144:147], v168
	ds_read_b128 v[148:151], v168 offset:1024
	ds_read_b128 v[164:167], v168 offset:2048
	ds_read_b128 v[174:177], v168 offset:3072
	ds_read_b128 v[178:181], v173
	ds_read_b128 v[182:185], v173 offset:1024
	ds_read_b128 v[186:189], v173 offset:2048
	ds_read_b128 v[194:197], v173 offset:3072
	ds_read_b128 v[202:205], v173 offset:4096
	ds_read_b128 v[206:209], v173 offset:5120
	ds_read_b128 v[210:213], v173 offset:6144
	ds_read_b128 v[214:217], v173 offset:7168
	s_add_i32 s58, s58, 1
	s_mul_i32 s0, s58, s57
	s_mul_hi_u32 s1, s58, s51
	s_add_i32 s1, s1, s0
	s_mul_i32 s0, s58, s51
	s_add_u32 s18, s0, s23
	v_readlane_b32 s0, v254, 44
	s_addc_u32 s19, s1, s0
	v_cmp_gt_i64_e32 vcc, s[18:19], v[200:201]
	v_cmp_lt_i64_e64 s[0:1], s[18:19], v[198:199]
	s_cbranch_vccnz .LBB0_634
	s_ashr_i32 s12, s18, 31
	s_lshr_b32 s12, s12, 29
	s_add_i32 s14, s18, s12
	s_and_b32 s12, s14, -8
	s_sub_i32 s15, s18, s12
	s_cmp_gt_i32 s15, -1
	s_mov_b64 s[12:13], -1
	s_cbranch_scc0 .LBB0_631
	s_lshl_b32 s18, s15, 6
	s_mov_b64 s[12:13], 0

; #define PG8_STAGE(bufoff, gbase, voff) do { _Pragma("unroll") for (int _i = 0; _i < 2; ++_i) \
;         __builtin_amdgcn_global_load_lds((const unsigned*)((const char*)(gbase) + (voff)[_i]), (PG8_LAS unsigned*)(lds + (bufoff) + ldsw + _i * 8192), 16, 0, 0); } while (0)
; #define PG8_LDA(dst, b, h) do { _Pragma("unroll") for (int m = 0; m < 4; ++m) _Pragma("unroll") for (int k = 0; k < 2; ++k) dst[m][k] = *(const PG8_LAS bf16x8*)(lds + PG8_SA(b, h) + aoff + m * 2048 + k * 1024); } while (0)
; #define PG8_LDB(dst, b, h) do { _Pragma("unroll") for (int n = 0; n < 2; ++n) _Pragma("unroll") for (int k = 0; k < 2; ++k) dst[n][k] = *(const PG8_LAS bf16x8*)(lds + PG8_SB(b, h) + boff + n * 2048 + k * 1024); } while (0)
; #define PG8_WAIT_V(n) asm volatile("s_waitcnt vmcnt(" #n ")" ::: "memory")
; #define PG8_WAIT_L(n) asm volatile("s_waitcnt lgkmcnt(" #n ")" ::: "memory")
; #define PG8_BAR __builtin_amdgcn_s_barrier()
; template <class Epi, class Sched, bool ALIGN_EPI = false, bool SP2 = false>
; __device__ __forceinline__ void gemm_phase(PG8_LAS unsigned char* lds, const Gemm g, const Sched& S, const Epi& E) {
;     ...
;         const bool has_next = S.next(ui + 1, nxt);
;         const char* nA = has_next ? (const char*)g.A + (size_t)nxt.pm * tstep : cA; const char* nB = has_next ? (const char*)g.Bt + (size_t)nxt.pn * tstep : cB;
;         for (int t = 0; t < nt; t += 2) {
;             if constexpr (Epi::MID_HOOK) { if (t == Epi::MID_T) E.mid(acc, cur, wr, wc, fr, fq); }
;             const bool last = (t == nt - 2);
;             const char* a1 = cA + (size_t)(t + 1) * kstep;
;             const char* a2 = last ? nA : cA + (size_t)(t + 2) * kstep; const char* b2 = last ? nB : cB + (size_t)(t + 2) * kstep;
;             const char* a3 = a2 + kstep; const char* b3 = b2 + kstep;
;             if (last && has_next) S.a_ready(nxt);
;             if constexpr (SP2) {
;             PG8_LDB(B0, 0, 0); PG8_LDB(B1, 0, 1); PG8_SCHED; PG8_LDA(At, 0, 0); PG8_STAGE(PG8_SA(1, 1), a1 + hstep, voffA);
;             PG8_WAIT_V(8); PG8_WAIT_L(0); PG8_BAR; PG8_MMA(0, 0, At, B0); PG8_MMA(0, 1, At, B1); PG8_BAR; PG8_SCHED;
;             PG8_LDA(At, 0, 1); PG8_STAGE(PG8_SB(0, 0), b2, voffB); PG8_STAGE(PG8_SB(0, 1), b2 + hstep, voffB); PG8_STAGE(PG8_SA(0, 0), a2, voffA);
;             PG8_WAIT_V(8); PG8_WAIT_L(0); PG8_BAR; PG8_MMA(1, 0, At, B0); PG8_MMA(1, 1, At, B1); PG8_BAR; PG8_SCHED;
.LBB0_634:
	s_ashr_i32 s15, s14, 31
	s_lshl_b64 s[18:19], s[14:15], 20
	s_add_u32 s18, s45, s18
	s_addc_u32 s19, s46, s19
	s_and_b64 s[30:31], s[0:1], exec
	s_cselect_b32 s15, s19, s37
	s_cselect_b32 s61, s18, s36
	s_ashr_i32 s13, s12, 31
	s_lshl_b64 s[30:31], s[12:13], 20
	s_add_u32 s30, s34, s30
	s_addc_u32 s31, s44, s31
	s_and_b64 s[42:43], s[0:1], exec
	s_cselect_b32 s13, s31, s39
	s_cselect_b32 s62, s30, s38
	s_add_u32 s36, s36, 0x80080
	s_addc_u32 s37, s37, 0
	s_add_u32 s63, s38, 0x100
	s_addc_u32 s64, s39, 0
	s_mov_b32 s65, -2
	s_waitcnt lgkmcnt(0)
	v_lshl_add_u64 v[168:169], s[36:37], 0, v[160:161]
	s_add_i32 m0, s2, 0xc000
	global_load_lds_dwordx4 v[168:169], off
	s_add_i32 m0, s2, 0xe000
	v_lshl_add_u64 v[168:169], s[36:37], 0, v[162:163]
	global_load_lds_dwordx4 v[168:169], off
	s_add_u32 s24, s36, 0xfff80080
	s_addc_u32 s25, s37, -1
	s_add_i32 s33, 0, 0x10000
	s_cmp_eq_u32 s65, 28
	s_cselect_b32 s43, s15, s25
	s_cselect_b32 s42, s61, s24
	s_cselect_b32 s39, s13, s64
	s_cselect_b32 s38, s62, s63
	s_add_i32 s24, 0, 0x14000
	s_waitcnt vmcnt(8)
	s_waitcnt lgkmcnt(0)
	s_barrier
	s_setprio 1
	s_waitcnt lgkmcnt(0)
	v_mfma_f32_16x16x32_bf16 v[124:127], v[128:131], v[178:181], 0
	v_mfma_f32_16x16x32_bf16 v[120:123], v[136:139], v[178:181], 0
	v_mfma_f32_16x16x32_bf16 v[108:111], v[128:131], v[186:189], 0
	v_mfma_f32_16x16x32_bf16 v[104:107], v[136:139], v[186:189], 0
	v_mfma_f32_16x16x32_bf16 v[92:95], v[128:131], v[202:205], 0
	v_mfma_f32_16x16x32_bf16 v[88:91], v[136:139], v[202:205], 0
	v_mfma_f32_16x16x32_bf16 v[76:79], v[128:131], v[210:213], 0
	v_mfma_f32_16x16x32_bf16 v[72:75], v[136:139], v[210:213], 0
	v_mfma_f32_16x16x32_bf16 v[124:127], v[132:135], v[182:185], v[124:127]
	v_mfma_f32_16x16x32_bf16 v[120:123], v[140:143], v[182:185], v[120:123]
	v_mfma_f32_16x16x32_bf16 v[108:111], v[132:135], v[194:197], v[108:111]
	v_mfma_f32_16x16x32_bf16 v[104:107], v[140:143], v[194:197], v[104:107]
	v_mfma_f32_16x16x32_bf16 v[92:95], v[132:135], v[206:209], v[92:95]
	v_mfma_f32_16x16x32_bf16 v[88:91], v[140:143], v[206:209], v[88:91]
	v_mfma_f32_16x16x32_bf16 v[76:79], v[132:135], v[214:217], v[76:79]
	v_mfma_f32_16x16x32_bf16 v[72:75], v[140:143], v[214:217], v[72:75]
	s_setprio 0
	s_setprio 1
	v_mfma_f32_16x16x32_bf16 v[116:119], v[144:147], v[178:181], 0
	v_mfma_f32_16x16x32_bf16 v[112:115], v[164:167], v[178:181], 0
	v_mfma_f32_16x16x32_bf16 v[100:103], v[144:147], v[186:189], 0
	v_mfma_f32_16x16x32_bf16 v[96:99], v[164:167], v[186:189], 0
	v_mfma_f32_16x16x32_bf16 v[84:87], v[144:147], v[202:205], 0
	v_mfma_f32_16x16x32_bf16 v[80:83], v[164:167], v[202:205], 0
	v_mfma_f32_16x16x32_bf16 v[68:71], v[144:147], v[210:213], 0
	v_mfma_f32_16x16x32_bf16 v[64:67], v[164:167], v[210:213], 0
	v_mfma_f32_16x16x32_bf16 v[116:119], v[148:151], v[182:185], v[116:119]
	v_mfma_f32_16x16x32_bf16 v[112:115], v[174:177], v[182:185], v[112:115]
	v_mfma_f32_16x16x32_bf16 v[100:103], v[148:151], v[194:197], v[100:103]
	v_mfma_f32_16x16x32_bf16 v[96:99], v[174:177], v[194:197], v[96:99]
	v_mfma_f32_16x16x32_bf16 v[84:87], v[148:151], v[206:209], v[84:87]
	v_mfma_f32_16x16x32_bf16 v[80:83], v[174:177], v[206:209], v[80:83]
	v_mfma_f32_16x16x32_bf16 v[68:71], v[148:151], v[214:217], v[68:71]
	v_mfma_f32_16x16x32_bf16 v[64:67], v[174:177], v[214:217], v[64:67]
	s_setprio 0
	s_barrier
	s_add_i32 s25, s33, s47
	v_lshl_add_u64 v[168:169], s[38:39], 0, v[156:157]
	s_mov_b32 m0, s25
	ds_read_b128 v[178:181], v173 offset:16384
	ds_read_b128 v[182:185], v173 offset:17408
	ds_read_b128 v[186:189], v173 offset:18432
	ds_read_b128 v[194:197], v173 offset:19456
	ds_read_b128 v[202:205], v173 offset:20480
	ds_read_b128 v[206:209], v173 offset:21504
	ds_read_b128 v[210:213], v173 offset:22528
	ds_read_b128 v[214:217], v173 offset:23552
	global_load_lds_dwordx4 v[168:169], off
	s_add_i32 m0, s25, 0x2000
	s_add_u32 s66, s38, 0x80000
	v_lshl_add_u64 v[190:191], s[38:39], 0, v[152:153]
	s_addc_u32 s67, s39, 0
	s_add_i32 s24, s24, s47
	global_load_lds_dwordx4 v[190:191], off
	v_lshl_add_u64 v[218:219], s[66:67], 0, v[156:157]
	s_mov_b32 m0, s24
	v_lshl_add_u64 v[220:221], s[42:43], 0, v[154:155]
	global_load_lds_dwordx4 v[218:219], off
	s_add_i32 m0, s24, 0x2000
	v_lshl_add_u64 v[218:219], s[66:67], 0, v[152:153]
	global_load_lds_dwordx4 v[218:219], off
	s_mov_b32 m0, s2
	v_lshl_add_u64 v[218:219], s[42:43], 0, v[158:159]
	global_load_lds_dwordx4 v[218:219], off
	s_mov_b32 m0, s48
	s_nop 0
	global_load_lds_dwordx4 v[220:221], off
	s_waitcnt vmcnt(8)
	s_waitcnt lgkmcnt(0)
	s_barrier
	s_setprio 1
	s_waitcnt lgkmcnt(0)
	v_mfma_f32_16x16x32_bf16 v[60:63], v[128:131], v[178:181], 0
	v_mfma_f32_16x16x32_bf16 v[56:59], v[136:139], v[178:181], 0
	v_mfma_f32_16x16x32_bf16 v[44:47], v[128:131], v[186:189], 0
	v_mfma_f32_16x16x32_bf16 v[40:43], v[136:139], v[186:189], 0
	v_mfma_f32_16x16x32_bf16 v[28:31], v[128:131], v[202:205], 0
	v_mfma_f32_16x16x32_bf16 v[24:27], v[136:139], v[202:205], 0
	v_mfma_f32_16x16x32_bf16 v[12:15], v[128:131], v[210:213], 0
	v_mfma_f32_16x16x32_bf16 v[8:11], v[136:139], v[210:213], 0
	v_mfma_f32_16x16x32_bf16 v[60:63], v[132:135], v[182:185], v[60:63]
	v_mfma_f32_16x16x32_bf16 v[56:59], v[140:143], v[182:185], v[56:59]
	v_mfma_f32_16x16x32_bf16 v[44:47], v[132:135], v[194:197], v[44:47]
	v_mfma_f32_16x16x32_bf16 v[40:43], v[140:143], v[194:197], v[40:43]
	v_mfma_f32_16x16x32_bf16 v[28:31], v[132:135], v[206:209], v[28:31]
	v_mfma_f32_16x16x32_bf16 v[24:27], v[140:143], v[206:209], v[24:27]
	v_mfma_f32_16x16x32_bf16 v[12:15], v[132:135], v[214:217], v[12:15]
	v_mfma_f32_16x16x32_bf16 v[8:11], v[140:143], v[214:217], v[8:11]
	s_setprio 0
	s_setprio 1
	v_mfma_f32_16x16x32_bf16 v[52:55], v[144:147], v[178:181], 0
	v_mfma_f32_16x16x32_bf16 v[48:51], v[164:167], v[178:181], 0
	v_mfma_f32_16x16x32_bf16 v[36:39], v[144:147], v[186:189], 0
	v_mfma_f32_16x16x32_bf16 v[32:35], v[164:167], v[186:189], 0
	v_mfma_f32_16x16x32_bf16 v[20:23], v[144:147], v[202:205], 0
	v_mfma_f32_16x16x32_bf16 v[16:19], v[164:167], v[202:205], 0
	v_mfma_f32_16x16x32_bf16 v[4:7], v[144:147], v[210:213], 0
	v_mfma_f32_16x16x32_bf16 v[0:3], v[164:167], v[210:213], 0
	v_mfma_f32_16x16x32_bf16 v[52:55], v[148:151], v[182:185], v[52:55]
	v_mfma_f32_16x16x32_bf16 v[48:51], v[174:177], v[182:185], v[48:51]
	v_mfma_f32_16x16x32_bf16 v[36:39], v[148:151], v[194:197], v[36:39]
	v_mfma_f32_16x16x32_bf16 v[32:35], v[174:177], v[194:197], v[32:35]
	v_mfma_f32_16x16x32_bf16 v[20:23], v[148:151], v[206:209], v[20:23]
	v_mfma_f32_16x16x32_bf16 v[16:19], v[174:177], v[206:209], v[16:19]
	v_mfma_f32_16x16x32_bf16 v[4:7], v[148:151], v[214:217], v[4:7]
	v_mfma_f32_16x16x32_bf16 v[0:3], v[174:177], v[214:217], v[0:3]
	s_setprio 0
	s_barrier
; #define PG8_STAGE(bufoff, gbase, voff) do { _Pragma("unroll") for (int _i = 0; _i < 2; ++_i) \
;         __builtin_amdgcn_global_load_lds((const unsigned*)((const char*)(gbase) + (voff)[_i]), (PG8_LAS unsigned*)(lds + (bufoff) + ldsw + _i * 8192), 16, 0, 0); } while (0)
; #define PG8_LDA(dst, b, h) do { _Pragma("unroll") for (int m = 0; m < 4; ++m) _Pragma("unroll") for (int k = 0; k < 2; ++k) dst[m][k] = *(const PG8_LAS bf16x8*)(lds + PG8_SA(b, h) + aoff + m * 2048 + k * 1024); } while (0)
; #define PG8_LDB(dst, b, h) do { _Pragma("unroll") for (int n = 0; n < 2; ++n) _Pragma("unroll") for (int k = 0; k < 2; ++k) dst[n][k] = *(const PG8_LAS bf16x8*)(lds + PG8_SB(b, h) + boff + n * 2048 + k * 1024); } while (0)
; #define PG8_MMA(ai, bj, At, Bt) do { __builtin_amdgcn_s_setprio(1); _Pragma("unroll") for (int m = 0; m < 4; ++m) _Pragma("unroll") for (int n = 0; n < 2; ++n) _Pragma("unroll") for (int k = 0; k < 2; ++k) \
;         acc[ai][bj][m][n] = __builtin_amdgcn_mfma_f32_16x16x32_bf16(Bt[n][k], At[m][k], acc[ai][bj][m][n], 0, 0, 0); __builtin_amdgcn_s_setprio(0); } while (0)
; #define PG8_WAIT_V(n) asm volatile("s_waitcnt vmcnt(" #n ")" ::: "memory")
; #define PG8_WAIT_L(n) asm volatile("s_waitcnt lgkmcnt(" #n ")" ::: "memory")
; #define PG8_BAR __builtin_amdgcn_s_barrier()
; #define PG8_SCHED __builtin_amdgcn_sched_barrier(0)
; template <class Epi, class Sched, bool ALIGN_EPI = false, bool SP2 = false>
; __device__ __forceinline__ void gemm_phase(PG8_LAS unsigned char* lds, const Gemm g, const Sched& S, const Epi& E) {
;     ...
;             PG8_LDB(B0, 1, 0); PG8_LDB(B1, 1, 1); PG8_SCHED; PG8_LDA(At, 1, 0); PG8_STAGE(PG8_SA(0, 1), a2 + hstep, voffA);
;             PG8_WAIT_V(8); PG8_WAIT_L(0); PG8_BAR; PG8_MMA(0, 0, At, B0); PG8_MMA(0, 1, At, B1); PG8_BAR; PG8_SCHED;
	s_add_i32 s24, 0, 0x18000
	s_add_i32 s25, 0, 0x1c000
	v_add_u32_e32 v140, 0x18000, v172
	v_add_u32_e32 v174, 0x1c000, v172
	ds_read_b128 v[128:131], v140
	ds_read_b128 v[132:135], v140 offset:1024
	ds_read_b128 v[136:139], v140 offset:2048
	ds_read_b128 v[140:143], v140 offset:3072
	ds_read_b128 v[144:147], v174
	ds_read_b128 v[148:151], v174 offset:1024
	ds_read_b128 v[164:167], v174 offset:2048
	ds_read_b128 v[174:177], v174 offset:3072
	s_add_u32 s42, s42, 0x80000
	s_addc_u32 s43, s43, 0
	s_mov_b32 m0, s49
	v_lshl_add_u64 v[230:231], s[42:43], 0, v[158:159]
	ds_read_b128 v[178:181], v173 offset:32768
	ds_read_b128 v[182:185], v173 offset:33792
	ds_read_b128 v[186:189], v173 offset:34816
	ds_read_b128 v[194:197], v173 offset:35840
	ds_read_b128 v[202:205], v173 offset:36864
	ds_read_b128 v[206:209], v173 offset:37888
	ds_read_b128 v[210:213], v173 offset:38912
	ds_read_b128 v[214:217], v173 offset:39936
	global_load_lds_dwordx4 v[230:231], off
	s_mov_b32 m0, s50
	v_lshl_add_u64 v[230:231], s[42:43], 0, v[154:155]
	global_load_lds_dwordx4 v[230:231], off
	s_waitcnt vmcnt(8)
	s_waitcnt lgkmcnt(0)
	s_barrier
	s_setprio 1
	s_waitcnt lgkmcnt(0)
	v_mfma_f32_16x16x32_bf16 v[124:127], v[128:131], v[178:181], v[124:127]
	v_mfma_f32_16x16x32_bf16 v[120:123], v[136:139], v[178:181], v[120:123]
	v_mfma_f32_16x16x32_bf16 v[108:111], v[128:131], v[186:189], v[108:111]
	v_mfma_f32_16x16x32_bf16 v[104:107], v[136:139], v[186:189], v[104:107]
	v_mfma_f32_16x16x32_bf16 v[92:95], v[128:131], v[202:205], v[92:95]
	v_mfma_f32_16x16x32_bf16 v[88:91], v[136:139], v[202:205], v[88:91]
	v_mfma_f32_16x16x32_bf16 v[76:79], v[128:131], v[210:213], v[76:79]
	v_mfma_f32_16x16x32_bf16 v[72:75], v[136:139], v[210:213], v[72:75]
	v_mfma_f32_16x16x32_bf16 v[124:127], v[132:135], v[182:185], v[124:127]
	v_mfma_f32_16x16x32_bf16 v[120:123], v[140:143], v[182:185], v[120:123]
	v_mfma_f32_16x16x32_bf16 v[108:111], v[132:135], v[194:197], v[108:111]
	v_mfma_f32_16x16x32_bf16 v[104:107], v[140:143], v[194:197], v[104:107]
	v_mfma_f32_16x16x32_bf16 v[92:95], v[132:135], v[206:209], v[92:95]
	v_mfma_f32_16x16x32_bf16 v[88:91], v[140:143], v[206:209], v[88:91]
	v_mfma_f32_16x16x32_bf16 v[76:79], v[132:135], v[214:217], v[76:79]
	v_mfma_f32_16x16x32_bf16 v[72:75], v[140:143], v[214:217], v[72:75]
	s_setprio 0
	s_setprio 1
	v_mfma_f32_16x16x32_bf16 v[116:119], v[144:147], v[178:181], v[116:119]
	v_mfma_f32_16x16x32_bf16 v[112:115], v[164:167], v[178:181], v[112:115]
	v_mfma_f32_16x16x32_bf16 v[100:103], v[144:147], v[186:189], v[100:103]
	v_mfma_f32_16x16x32_bf16 v[96:99], v[164:167], v[186:189], v[96:99]
	v_mfma_f32_16x16x32_bf16 v[84:87], v[144:147], v[202:205], v[84:87]
	v_mfma_f32_16x16x32_bf16 v[80:83], v[164:167], v[202:205], v[80:83]
	v_mfma_f32_16x16x32_bf16 v[68:71], v[144:147], v[210:213], v[68:71]
	v_mfma_f32_16x16x32_bf16 v[64:67], v[164:167], v[210:213], v[64:67]
	v_mfma_f32_16x16x32_bf16 v[116:119], v[148:151], v[182:185], v[116:119]
	v_mfma_f32_16x16x32_bf16 v[112:115], v[174:177], v[182:185], v[112:115]
	v_mfma_f32_16x16x32_bf16 v[100:103], v[148:151], v[194:197], v[100:103]
	v_mfma_f32_16x16x32_bf16 v[96:99], v[174:177], v[194:197], v[96:99]
	v_mfma_f32_16x16x32_bf16 v[84:87], v[148:151], v[206:209], v[84:87]
	v_mfma_f32_16x16x32_bf16 v[80:83], v[174:177], v[206:209], v[80:83]
	v_mfma_f32_16x16x32_bf16 v[68:71], v[148:151], v[214:217], v[68:71]
	v_mfma_f32_16x16x32_bf16 v[64:67], v[174:177], v[214:217], v[64:67]
	s_setprio 0
	s_barrier
; #define PG8_STAGE(bufoff, gbase, voff) do { _Pragma("unroll") for (int _i = 0; _i < 2; ++_i) \
;         __builtin_amdgcn_global_load_lds((const unsigned*)((const char*)(gbase) + (voff)[_i]), (PG8_LAS unsigned*)(lds + (bufoff) + ldsw + _i * 8192), 16, 0, 0); } while (0)
; #define PG8_LDA(dst, b, h) do { _Pragma("unroll") for (int m = 0; m < 4; ++m) _Pragma("unroll") for (int k = 0; k < 2; ++k) dst[m][k] = *(const PG8_LAS bf16x8*)(lds + PG8_SA(b, h) + aoff + m * 2048 + k * 1024); } while (0)
; #define PG8_MMA(ai, bj, At, Bt) do { __builtin_amdgcn_s_setprio(1); _Pragma("unroll") for (int m = 0; m < 4; ++m) _Pragma("unroll") for (int n = 0; n < 2; ++n) _Pragma("unroll") for (int k = 0; k < 2; ++k) \
;         acc[ai][bj][m][n] = __builtin_amdgcn_mfma_f32_16x16x32_bf16(Bt[n][k], At[m][k], acc[ai][bj][m][n], 0, 0, 0); __builtin_amdgcn_s_setprio(0); } while (0)
; #define PG8_WAIT_V(n) asm volatile("s_waitcnt vmcnt(" #n ")" ::: "memory")
; #define PG8_WAIT_L(n) asm volatile("s_waitcnt lgkmcnt(" #n ")" ::: "memory")
; #define PG8_BAR __builtin_amdgcn_s_barrier()
; #define PG8_SCHED __builtin_amdgcn_sched_barrier(0)
; template <class Epi, class Sched, bool ALIGN_EPI = false, bool SP2 = false>
; __device__ __forceinline__ void gemm_phase(PG8_LAS unsigned char* lds, const Gemm g, const Sched& S, const Epi& E) {
;     ...
;             PG8_LDA(At, 1, 1); PG8_STAGE(PG8_SB(1, 0), b3, voffB); PG8_STAGE(PG8_SB(1, 1), b3 + hstep, voffB); PG8_STAGE(PG8_SA(1, 0), a3, voffA);
;             PG8_WAIT_V(8); PG8_WAIT_L(0); PG8_BAR; PG8_MMA(1, 0, At, B0); PG8_MMA(1, 1, At, B1); PG8_BAR; PG8_SCHED;
	s_add_i32 s24, s24, s47
	v_lshl_add_u64 v[168:169], v[168:169], 0, s[16:17]
	s_mov_b32 m0, s24
	ds_read_b128 v[178:181], v173 offset:49152
	ds_read_b128 v[182:185], v173 offset:50176
	ds_read_b128 v[186:189], v173 offset:51200
	ds_read_b128 v[194:197], v173 offset:52224
	ds_read_b128 v[202:205], v173 offset:53248
	ds_read_b128 v[206:209], v173 offset:54272
	ds_read_b128 v[210:213], v173 offset:55296
	ds_read_b128 v[214:217], v173 offset:56320
	global_load_lds_dwordx4 v[168:169], off
	s_add_i32 m0, s24, 0x2000
	s_add_u32 s38, s38, 0x80080
	v_lshl_add_u64 v[168:169], v[190:191], 0, s[16:17]
	s_addc_u32 s39, s39, 0
	s_add_i32 s24, s25, s47
	global_load_lds_dwordx4 v[168:169], off
	s_mov_b32 m0, s24
	v_lshl_add_u64 v[168:169], s[38:39], 0, v[156:157]
	global_load_lds_dwordx4 v[168:169], off
	s_add_i32 m0, s24, 0x2000
	v_lshl_add_u64 v[168:169], s[38:39], 0, v[152:153]
	global_load_lds_dwordx4 v[168:169], off
	s_mov_b32 m0, s55
	v_lshl_add_u64 v[168:169], v[218:219], 0, s[16:17]
	global_load_lds_dwordx4 v[168:169], off
	s_mov_b32 m0, s56
	v_lshl_add_u64 v[168:169], v[220:221], 0, s[16:17]
	global_load_lds_dwordx4 v[168:169], off
	s_waitcnt vmcnt(8)
	s_waitcnt lgkmcnt(0)
	s_barrier
	s_setprio 1
	s_waitcnt lgkmcnt(0)
	v_mfma_f32_16x16x32_bf16 v[60:63], v[128:131], v[178:181], v[60:63]
	v_mfma_f32_16x16x32_bf16 v[56:59], v[136:139], v[178:181], v[56:59]
	v_mfma_f32_16x16x32_bf16 v[44:47], v[128:131], v[186:189], v[44:47]
	v_mfma_f32_16x16x32_bf16 v[40:43], v[136:139], v[186:189], v[40:43]
	v_mfma_f32_16x16x32_bf16 v[28:31], v[128:131], v[202:205], v[28:31]
	v_mfma_f32_16x16x32_bf16 v[24:27], v[136:139], v[202:205], v[24:27]
	v_mfma_f32_16x16x32_bf16 v[12:15], v[128:131], v[210:213], v[12:15]
	v_mfma_f32_16x16x32_bf16 v[8:11], v[136:139], v[210:213], v[8:11]
	v_mfma_f32_16x16x32_bf16 v[60:63], v[132:135], v[182:185], v[60:63]
	v_mfma_f32_16x16x32_bf16 v[56:59], v[140:143], v[182:185], v[56:59]
	v_mfma_f32_16x16x32_bf16 v[44:47], v[132:135], v[194:197], v[44:47]
	v_mfma_f32_16x16x32_bf16 v[40:43], v[140:143], v[194:197], v[40:43]
	v_mfma_f32_16x16x32_bf16 v[28:31], v[132:135], v[206:209], v[28:31]
	v_mfma_f32_16x16x32_bf16 v[24:27], v[140:143], v[206:209], v[24:27]
	v_mfma_f32_16x16x32_bf16 v[12:15], v[132:135], v[214:217], v[12:15]
	v_mfma_f32_16x16x32_bf16 v[8:11], v[140:143], v[214:217], v[8:11]
	s_setprio 0
	s_setprio 1
	v_mfma_f32_16x16x32_bf16 v[52:55], v[144:147], v[178:181], v[52:55]
	v_mfma_f32_16x16x32_bf16 v[48:51], v[164:167], v[178:181], v[48:51]
	v_mfma_f32_16x16x32_bf16 v[36:39], v[144:147], v[186:189], v[36:39]
	v_mfma_f32_16x16x32_bf16 v[32:35], v[164:167], v[186:189], v[32:35]
	v_mfma_f32_16x16x32_bf16 v[20:23], v[144:147], v[202:205], v[20:23]
	v_mfma_f32_16x16x32_bf16 v[16:19], v[164:167], v[202:205], v[16:19]
	v_mfma_f32_16x16x32_bf16 v[4:7], v[144:147], v[210:213], v[4:7]
	v_mfma_f32_16x16x32_bf16 v[0:3], v[164:167], v[210:213], v[0:3]
	v_mfma_f32_16x16x32_bf16 v[52:55], v[148:151], v[182:185], v[52:55]
	v_mfma_f32_16x16x32_bf16 v[48:51], v[174:177], v[182:185], v[48:51]
	v_mfma_f32_16x16x32_bf16 v[36:39], v[148:151], v[194:197], v[36:39]
	v_mfma_f32_16x16x32_bf16 v[32:35], v[174:177], v[194:197], v[32:35]
	v_mfma_f32_16x16x32_bf16 v[20:23], v[148:151], v[206:209], v[20:23]
	v_mfma_f32_16x16x32_bf16 v[16:19], v[174:177], v[206:209], v[16:19]
	v_mfma_f32_16x16x32_bf16 v[4:7], v[148:151], v[214:217], v[4:7]
	v_mfma_f32_16x16x32_bf16 v[0:3], v[174:177], v[214:217], v[0:3]
	s_setprio 0
	s_barrier
	s_add_i32 s65, s65, 2
	s_add_u32 s36, s36, 0x100
	s_addc_u32 s37, s37, 0
	s_add_u32 s63, s63, 0x100
	s_addc_u32 s64, s64, 0
	s_cmp_gt_u32 s65, 29
	s_branch .LBB0_635

; #define PG8_STAGE(bufoff, gbase, voff) do { _Pragma("unroll") for (int _i = 0; _i < 2; ++_i) \
;         __builtin_amdgcn_global_load_lds((const unsigned*)((const char*)(gbase) + (voff)[_i]), (PG8_LAS unsigned*)(lds + (bufoff) + ldsw + _i * 8192), 16, 0, 0); } while (0)
; #define PG8_LDA(dst, b, h) do { _Pragma("unroll") for (int m = 0; m < 4; ++m) _Pragma("unroll") for (int k = 0; k < 2; ++k) dst[m][k] = *(const PG8_LAS bf16x8*)(lds + PG8_SA(b, h) + aoff + m * 2048 + k * 1024); } while (0)
; #define PG8_LDB(dst, b, h) do { _Pragma("unroll") for (int n = 0; n < 2; ++n) _Pragma("unroll") for (int k = 0; k < 2; ++k) dst[n][k] = *(const PG8_LAS bf16x8*)(lds + PG8_SB(b, h) + boff + n * 2048 + k * 1024); } while (0)
; #define PG8_SCHED __builtin_amdgcn_sched_barrier(0)
; template <class Epi, class Sched, bool ALIGN_EPI = false, bool SP2 = false>
; __device__ __forceinline__ void gemm_phase(PG8_LAS unsigned char* lds, const Gemm g, const Sched& S, const Epi& E) {
;     ...
;         const bool has_next = S.next(ui + 1, nxt);
;         const char* nA = has_next ? (const char*)g.A + (size_t)nxt.pm * tstep : cA; const char* nB = has_next ? (const char*)g.Bt + (size_t)nxt.pn * tstep : cB;
;         for (int t = 0; t < nt; t += 2) {
;             if constexpr (Epi::MID_HOOK) { if (t == Epi::MID_T) E.mid(acc, cur, wr, wc, fr, fq); }
;             const bool last = (t == nt - 2);
;             const char* a1 = cA + (size_t)(t + 1) * kstep;
;             const char* a2 = last ? nA : cA + (size_t)(t + 2) * kstep; const char* b2 = last ? nB : cB + (size_t)(t + 2) * kstep;
;             const char* a3 = a2 + kstep; const char* b3 = b2 + kstep;
;             if (last && has_next) S.a_ready(nxt);
;             if constexpr (SP2) {
;             PG8_LDB(B0, 0, 0); PG8_LDB(B1, 0, 1); PG8_SCHED; PG8_LDA(At, 0, 0); PG8_STAGE(PG8_SA(1, 1), a1 + hstep, voffA);
.LBB0_727:
	v_add_u32_e32 v148, 0x10000, v151
	ds_read_b128 v[140:143], v148
	ds_read_b128 v[144:147], v148 offset:1024
	ds_read_b128 v[154:157], v148 offset:2048
	ds_read_b128 v[158:161], v148 offset:3072
	v_add_u32_e32 v148, 0x14000, v151
	ds_read_b128 v[162:165], v148
	ds_read_b128 v[166:169], v148 offset:1024
	ds_read_b128 v[170:173], v148 offset:2048
	ds_read_b128 v[174:177], v148 offset:3072
	ds_read_b128 v[178:181], v152
	ds_read_b128 v[182:185], v152 offset:1024
	ds_read_b128 v[186:189], v152 offset:2048
	ds_read_b128 v[194:197], v152 offset:3072
	ds_read_b128 v[202:205], v152 offset:4096
	ds_read_b128 v[206:209], v152 offset:5120
	ds_read_b128 v[210:213], v152 offset:6144
	ds_read_b128 v[214:217], v152 offset:7168
	s_add_i32 s58, s58, 1
	s_mul_i32 s12, s58, s55
	s_mul_hi_u32 s13, s58, s38
	s_add_i32 s13, s13, s12
	s_mul_i32 s12, s58, s38
	s_add_u32 s12, s12, s23
	v_readlane_b32 s24, v254, 44
	s_addc_u32 s13, s13, s24
	v_cmp_gt_i64_e32 vcc, s[12:13], v[244:245]
	v_cmp_lt_i64_e64 s[42:43], s[12:13], v[242:243]
	s_cbranch_vccnz .LBB0_729
	s_cmp_lg_u32 s38, 0x100
	s_cbranch_scc1 .Lnx8_gen
	s_lshr_b32 s13, s12, 8
	s_lshl_b32 s13, s13, 2
	s_bfe_u32 s24, s12, 0x20006
	s_add_i32 s46, s13, s24
	s_and_b32 s13, s12, 7
	s_lshl_b32 s13, s13, 3
	s_bfe_u32 s24, s12, 0x30003
	s_add_i32 s48, s13, s24
	s_branch .LBB0_729

; #define PG8_STAGE(bufoff, gbase, voff) do { _Pragma("unroll") for (int _i = 0; _i < 2; ++_i) \
;         __builtin_amdgcn_global_load_lds((const unsigned*)((const char*)(gbase) + (voff)[_i]), (PG8_LAS unsigned*)(lds + (bufoff) + ldsw + _i * 8192), 16, 0, 0); } while (0)
; #define PG8_LDA(dst, b, h) do { _Pragma("unroll") for (int m = 0; m < 4; ++m) _Pragma("unroll") for (int k = 0; k < 2; ++k) dst[m][k] = *(const PG8_LAS bf16x8*)(lds + PG8_SA(b, h) + aoff + m * 2048 + k * 1024); } while (0)
; #define PG8_LDB(dst, b, h) do { _Pragma("unroll") for (int n = 0; n < 2; ++n) _Pragma("unroll") for (int k = 0; k < 2; ++k) dst[n][k] = *(const PG8_LAS bf16x8*)(lds + PG8_SB(b, h) + boff + n * 2048 + k * 1024); } while (0)
; #define PG8_WAIT_V(n) asm volatile("s_waitcnt vmcnt(" #n ")" ::: "memory")
; #define PG8_WAIT_L(n) asm volatile("s_waitcnt lgkmcnt(" #n ")" ::: "memory")
; #define PG8_BAR __builtin_amdgcn_s_barrier()
; #define PG8_SCHED __builtin_amdgcn_sched_barrier(0)
; template <class Epi, class Sched, bool ALIGN_EPI = false, bool SP2 = false>
; __device__ __forceinline__ void gemm_phase(PG8_LAS unsigned char* lds, const Gemm g, const Sched& S, const Epi& E) {
;     ...
;         const char* nA = has_next ? (const char*)g.A + (size_t)nxt.pm * tstep : cA; const char* nB = has_next ? (const char*)g.Bt + (size_t)nxt.pn * tstep : cB;
;         for (int t = 0; t < nt; t += 2) {
;             if constexpr (Epi::MID_HOOK) { if (t == Epi::MID_T) E.mid(acc, cur, wr, wc, fr, fq); }
;             const bool last = (t == nt - 2);
;             const char* a1 = cA + (size_t)(t + 1) * kstep;
;             const char* a2 = last ? nA : cA + (size_t)(t + 2) * kstep; const char* b2 = last ? nB : cB + (size_t)(t + 2) * kstep;
;             const char* a3 = a2 + kstep; const char* b3 = b2 + kstep;
;             if (last && has_next) S.a_ready(nxt);
;             if constexpr (SP2) {
;             PG8_LDB(B0, 0, 0); PG8_LDB(B1, 0, 1); PG8_SCHED; PG8_LDA(At, 0, 0); PG8_STAGE(PG8_SA(1, 1), a1 + hstep, voffA);
;             PG8_WAIT_V(8); PG8_WAIT_L(0); PG8_BAR; PG8_MMA(0, 0, At, B0); PG8_MMA(0, 1, At, B1); PG8_BAR; PG8_SCHED;
;             PG8_LDA(At, 0, 1); PG8_STAGE(PG8_SB(0, 0), b2, voffB); PG8_STAGE(PG8_SB(0, 1), b2 + hstep, voffB); PG8_STAGE(PG8_SA(0, 0), a2, voffA);
;             PG8_WAIT_V(8); PG8_WAIT_L(0); PG8_BAR; PG8_MMA(1, 0, At, B0); PG8_MMA(1, 1, At, B1); PG8_BAR; PG8_SCHED;
.LBB0_729:
	s_ashr_i32 s49, s48, 31
	s_lshl_b64 s[12:13], s[48:49], 20
	s_add_u32 s50, s18, s12
	s_addc_u32 s51, s19, s13
	s_and_b64 s[12:13], s[42:43], exec
	s_cselect_b32 s49, s51, s1
	s_cselect_b32 s60, s50, s0
	s_ashr_i32 s47, s46, 31
	s_lshl_b64 s[12:13], s[46:47], 20
	s_add_u32 s52, s14, s12
	s_addc_u32 s53, s15, s13
	s_and_b64 s[12:13], s[42:43], exec
	s_cselect_b32 s47, s53, s11
	s_cselect_b32 s61, s52, s10
	s_add_u32 s0, s0, 0x80080
	s_addc_u32 s1, s1, 0
	s_add_u32 s62, s10, 0x100
	s_addc_u32 s63, s11, 0
	s_mov_b32 s64, -2
	v_lshl_add_u64 v[190:191], s[0:1], 0, v[136:137]
	s_add_i32 m0, s31, 0xc000
	global_load_lds_dwordx4 v[190:191], off
	s_add_i32 m0, s31, 0xe000
	v_lshl_add_u64 v[190:191], s[0:1], 0, v[138:139]
	global_load_lds_dwordx4 v[190:191], off
	s_add_u32 s10, s0, 0xfff80080
	s_addc_u32 s11, s1, -1
	s_add_i32 s24, 0, 0x10000
	s_cmp_eq_u32 s64, 28
	s_cselect_b32 s13, s49, s11
	s_cselect_b32 s12, s60, s10
	s_cselect_b32 s11, s47, s63
	s_cselect_b32 s10, s61, s62
	s_add_i32 s25, 0, 0x14000
	s_waitcnt vmcnt(8)
	s_waitcnt lgkmcnt(0)
	s_barrier
	s_setprio 1
	s_waitcnt lgkmcnt(0)
	v_mfma_f32_16x16x32_bf16 v[124:127], v[140:143], v[178:181], 0
	v_mfma_f32_16x16x32_bf16 v[112:115], v[154:157], v[178:181], 0
	v_mfma_f32_16x16x32_bf16 v[108:111], v[140:143], v[186:189], 0
	v_mfma_f32_16x16x32_bf16 v[100:103], v[154:157], v[186:189], 0
	v_mfma_f32_16x16x32_bf16 v[92:95], v[140:143], v[202:205], 0
	v_mfma_f32_16x16x32_bf16 v[84:87], v[154:157], v[202:205], 0
	v_mfma_f32_16x16x32_bf16 v[76:79], v[140:143], v[210:213], 0
	v_mfma_f32_16x16x32_bf16 v[68:71], v[154:157], v[210:213], 0
	v_mfma_f32_16x16x32_bf16 v[124:127], v[144:147], v[182:185], v[124:127]
	v_mfma_f32_16x16x32_bf16 v[112:115], v[158:161], v[182:185], v[112:115]
	v_mfma_f32_16x16x32_bf16 v[108:111], v[144:147], v[194:197], v[108:111]
	v_mfma_f32_16x16x32_bf16 v[100:103], v[158:161], v[194:197], v[100:103]
	v_mfma_f32_16x16x32_bf16 v[92:95], v[144:147], v[206:209], v[92:95]
	v_mfma_f32_16x16x32_bf16 v[84:87], v[158:161], v[206:209], v[84:87]
	v_mfma_f32_16x16x32_bf16 v[76:79], v[144:147], v[214:217], v[76:79]
	v_mfma_f32_16x16x32_bf16 v[68:71], v[158:161], v[214:217], v[68:71]
	s_setprio 0
	s_setprio 1
	v_mfma_f32_16x16x32_bf16 v[120:123], v[162:165], v[178:181], 0
	v_mfma_f32_16x16x32_bf16 v[116:119], v[170:173], v[178:181], 0
	v_mfma_f32_16x16x32_bf16 v[104:107], v[162:165], v[186:189], 0
	v_mfma_f32_16x16x32_bf16 v[96:99], v[170:173], v[186:189], 0
	v_mfma_f32_16x16x32_bf16 v[88:91], v[162:165], v[202:205], 0
	v_mfma_f32_16x16x32_bf16 v[80:83], v[170:173], v[202:205], 0
	v_mfma_f32_16x16x32_bf16 v[72:75], v[162:165], v[210:213], 0
	v_mfma_f32_16x16x32_bf16 v[64:67], v[170:173], v[210:213], 0
	v_mfma_f32_16x16x32_bf16 v[120:123], v[166:169], v[182:185], v[120:123]
	v_mfma_f32_16x16x32_bf16 v[116:119], v[174:177], v[182:185], v[116:119]
	v_mfma_f32_16x16x32_bf16 v[104:107], v[166:169], v[194:197], v[104:107]
	v_mfma_f32_16x16x32_bf16 v[96:99], v[174:177], v[194:197], v[96:99]
	v_mfma_f32_16x16x32_bf16 v[88:91], v[166:169], v[206:209], v[88:91]
	v_mfma_f32_16x16x32_bf16 v[80:83], v[174:177], v[206:209], v[80:83]
	v_mfma_f32_16x16x32_bf16 v[72:75], v[166:169], v[214:217], v[72:75]
	v_mfma_f32_16x16x32_bf16 v[64:67], v[174:177], v[214:217], v[64:67]
	s_setprio 0
	s_barrier
	s_add_i32 s24, s24, s30
	v_lshl_add_u64 v[190:191], s[10:11], 0, v[132:133]
	s_mov_b32 m0, s24
	ds_read_b128 v[178:181], v152 offset:16384
	ds_read_b128 v[182:185], v152 offset:17408
	ds_read_b128 v[186:189], v152 offset:18432
	ds_read_b128 v[194:197], v152 offset:19456
	ds_read_b128 v[202:205], v152 offset:20480
	ds_read_b128 v[206:209], v152 offset:21504
	ds_read_b128 v[210:213], v152 offset:22528
	ds_read_b128 v[214:217], v152 offset:23552
	global_load_lds_dwordx4 v[190:191], off
	s_add_i32 m0, s24, 0x2000
	s_add_u32 s66, s10, 0x80000
	v_lshl_add_u64 v[218:219], s[10:11], 0, v[128:129]
	s_addc_u32 s67, s11, 0
	s_add_i32 s24, s25, s30
	global_load_lds_dwordx4 v[218:219], off
	v_lshl_add_u64 v[220:221], s[66:67], 0, v[132:133]
	s_mov_b32 m0, s24
	v_lshl_add_u64 v[230:231], s[12:13], 0, v[130:131]
	global_load_lds_dwordx4 v[220:221], off
	s_add_i32 m0, s24, 0x2000
	v_lshl_add_u64 v[220:221], s[66:67], 0, v[128:129]
	global_load_lds_dwordx4 v[220:221], off
	s_mov_b32 m0, s31
	v_lshl_add_u64 v[220:221], s[12:13], 0, v[134:135]
	global_load_lds_dwordx4 v[220:221], off
	s_mov_b32 m0, s34
	s_nop 0
	global_load_lds_dwordx4 v[230:231], off
	s_waitcnt vmcnt(8)
	s_waitcnt lgkmcnt(0)
	s_barrier
	s_setprio 1
	s_waitcnt lgkmcnt(0)
	v_mfma_f32_16x16x32_bf16 v[60:63], v[140:143], v[178:181], 0
	v_mfma_f32_16x16x32_bf16 v[52:55], v[154:157], v[178:181], 0
	v_mfma_f32_16x16x32_bf16 v[44:47], v[140:143], v[186:189], 0
	v_mfma_f32_16x16x32_bf16 v[36:39], v[154:157], v[186:189], 0
	v_mfma_f32_16x16x32_bf16 v[28:31], v[140:143], v[202:205], 0
	v_mfma_f32_16x16x32_bf16 v[20:23], v[154:157], v[202:205], 0
	v_mfma_f32_16x16x32_bf16 v[12:15], v[140:143], v[210:213], 0
	v_mfma_f32_16x16x32_bf16 v[4:7], v[154:157], v[210:213], 0
	v_mfma_f32_16x16x32_bf16 v[60:63], v[144:147], v[182:185], v[60:63]
	v_mfma_f32_16x16x32_bf16 v[52:55], v[158:161], v[182:185], v[52:55]
	v_mfma_f32_16x16x32_bf16 v[44:47], v[144:147], v[194:197], v[44:47]
	v_mfma_f32_16x16x32_bf16 v[36:39], v[158:161], v[194:197], v[36:39]
	v_mfma_f32_16x16x32_bf16 v[28:31], v[144:147], v[206:209], v[28:31]
	v_mfma_f32_16x16x32_bf16 v[20:23], v[158:161], v[206:209], v[20:23]
	v_mfma_f32_16x16x32_bf16 v[12:15], v[144:147], v[214:217], v[12:15]
	v_mfma_f32_16x16x32_bf16 v[4:7], v[158:161], v[214:217], v[4:7]
	s_setprio 0
	s_setprio 1
	v_mfma_f32_16x16x32_bf16 v[56:59], v[162:165], v[178:181], 0
	v_mfma_f32_16x16x32_bf16 v[48:51], v[170:173], v[178:181], 0
	v_mfma_f32_16x16x32_bf16 v[40:43], v[162:165], v[186:189], 0
	v_mfma_f32_16x16x32_bf16 v[32:35], v[170:173], v[186:189], 0
	v_mfma_f32_16x16x32_bf16 v[24:27], v[162:165], v[202:205], 0
	v_mfma_f32_16x16x32_bf16 v[16:19], v[170:173], v[202:205], 0
	v_mfma_f32_16x16x32_bf16 v[8:11], v[162:165], v[210:213], 0
	v_mfma_f32_16x16x32_bf16 v[0:3], v[170:173], v[210:213], 0
	v_mfma_f32_16x16x32_bf16 v[56:59], v[166:169], v[182:185], v[56:59]
	v_mfma_f32_16x16x32_bf16 v[48:51], v[174:177], v[182:185], v[48:51]
	v_mfma_f32_16x16x32_bf16 v[40:43], v[166:169], v[194:197], v[40:43]
	v_mfma_f32_16x16x32_bf16 v[32:35], v[174:177], v[194:197], v[32:35]
	v_mfma_f32_16x16x32_bf16 v[24:27], v[166:169], v[206:209], v[24:27]
	v_mfma_f32_16x16x32_bf16 v[16:19], v[174:177], v[206:209], v[16:19]
	v_mfma_f32_16x16x32_bf16 v[8:11], v[166:169], v[214:217], v[8:11]
	v_mfma_f32_16x16x32_bf16 v[0:3], v[174:177], v[214:217], v[0:3]
	s_setprio 0
	s_barrier
; #define PG8_STAGE(bufoff, gbase, voff) do { _Pragma("unroll") for (int _i = 0; _i < 2; ++_i) \
;         __builtin_amdgcn_global_load_lds((const unsigned*)((const char*)(gbase) + (voff)[_i]), (PG8_LAS unsigned*)(lds + (bufoff) + ldsw + _i * 8192), 16, 0, 0); } while (0)
; #define PG8_LDA(dst, b, h) do { _Pragma("unroll") for (int m = 0; m < 4; ++m) _Pragma("unroll") for (int k = 0; k < 2; ++k) dst[m][k] = *(const PG8_LAS bf16x8*)(lds + PG8_SA(b, h) + aoff + m * 2048 + k * 1024); } while (0)
; #define PG8_LDB(dst, b, h) do { _Pragma("unroll") for (int n = 0; n < 2; ++n) _Pragma("unroll") for (int k = 0; k < 2; ++k) dst[n][k] = *(const PG8_LAS bf16x8*)(lds + PG8_SB(b, h) + boff + n * 2048 + k * 1024); } while (0)
; #define PG8_MMA(ai, bj, At, Bt) do { __builtin_amdgcn_s_setprio(1); _Pragma("unroll") for (int m = 0; m < 4; ++m) _Pragma("unroll") for (int n = 0; n < 2; ++n) _Pragma("unroll") for (int k = 0; k < 2; ++k) \
;         acc[ai][bj][m][n] = __builtin_amdgcn_mfma_f32_16x16x32_bf16(Bt[n][k], At[m][k], acc[ai][bj][m][n], 0, 0, 0); __builtin_amdgcn_s_setprio(0); } while (0)
; #define PG8_WAIT_V(n) asm volatile("s_waitcnt vmcnt(" #n ")" ::: "memory")
; #define PG8_WAIT_L(n) asm volatile("s_waitcnt lgkmcnt(" #n ")" ::: "memory")
; #define PG8_BAR __builtin_amdgcn_s_barrier()
; #define PG8_SCHED __builtin_amdgcn_sched_barrier(0)
; template <class Epi, class Sched, bool ALIGN_EPI = false, bool SP2 = false>
; __device__ __forceinline__ void gemm_phase(PG8_LAS unsigned char* lds, const Gemm g, const Sched& S, const Epi& E) {
;     ...
;             PG8_LDB(B0, 1, 0); PG8_LDB(B1, 1, 1); PG8_SCHED; PG8_LDA(At, 1, 0); PG8_STAGE(PG8_SA(0, 1), a2 + hstep, voffA);
;             PG8_WAIT_V(8); PG8_WAIT_L(0); PG8_BAR; PG8_MMA(0, 0, At, B0); PG8_MMA(0, 1, At, B1); PG8_BAR; PG8_SCHED;
;             PG8_LDA(At, 1, 1); PG8_STAGE(PG8_SB(1, 0), b3, voffB); PG8_STAGE(PG8_SB(1, 1), b3 + hstep, voffB); PG8_STAGE(PG8_SA(1, 0), a3, voffA);
;             PG8_WAIT_V(8); PG8_WAIT_L(0); PG8_BAR; PG8_MMA(1, 0, At, B0); PG8_MMA(1, 1, At, B1); PG8_BAR; PG8_SCHED;
	s_add_i32 s24, 0, 0x18000
	v_add_u32_e32 v148, 0x18000, v151
	s_add_i32 s25, 0, 0x1c000
	ds_read_b128 v[140:143], v148
	ds_read_b128 v[144:147], v148 offset:1024
	ds_read_b128 v[154:157], v148 offset:2048
	ds_read_b128 v[158:161], v148 offset:3072
	v_add_u32_e32 v148, 0x1c000, v151
	ds_read_b128 v[162:165], v148
	ds_read_b128 v[166:169], v148 offset:1024
	ds_read_b128 v[170:173], v148 offset:2048
	ds_read_b128 v[174:177], v148 offset:3072
	s_add_u32 s12, s12, 0x80000
	s_addc_u32 s13, s13, 0
	s_mov_b32 m0, s36
	v_lshl_add_u64 v[232:233], s[12:13], 0, v[134:135]
	ds_read_b128 v[178:181], v152 offset:32768
	ds_read_b128 v[182:185], v152 offset:33792
	ds_read_b128 v[186:189], v152 offset:34816
	ds_read_b128 v[194:197], v152 offset:35840
	ds_read_b128 v[202:205], v152 offset:36864
	ds_read_b128 v[206:209], v152 offset:37888
	ds_read_b128 v[210:213], v152 offset:38912
	ds_read_b128 v[214:217], v152 offset:39936
	global_load_lds_dwordx4 v[232:233], off
	s_mov_b32 m0, s37
	v_lshl_add_u64 v[232:233], s[12:13], 0, v[130:131]
	global_load_lds_dwordx4 v[232:233], off
	s_waitcnt vmcnt(8)
	s_waitcnt lgkmcnt(0)
	s_barrier
	s_setprio 1
	s_waitcnt lgkmcnt(0)
	v_mfma_f32_16x16x32_bf16 v[124:127], v[140:143], v[178:181], v[124:127]
	v_mfma_f32_16x16x32_bf16 v[112:115], v[154:157], v[178:181], v[112:115]
	v_mfma_f32_16x16x32_bf16 v[108:111], v[140:143], v[186:189], v[108:111]
	v_mfma_f32_16x16x32_bf16 v[100:103], v[154:157], v[186:189], v[100:103]
	v_mfma_f32_16x16x32_bf16 v[92:95], v[140:143], v[202:205], v[92:95]
	v_mfma_f32_16x16x32_bf16 v[84:87], v[154:157], v[202:205], v[84:87]
	v_mfma_f32_16x16x32_bf16 v[76:79], v[140:143], v[210:213], v[76:79]
	v_mfma_f32_16x16x32_bf16 v[68:71], v[154:157], v[210:213], v[68:71]
	v_mfma_f32_16x16x32_bf16 v[124:127], v[144:147], v[182:185], v[124:127]
	v_mfma_f32_16x16x32_bf16 v[112:115], v[158:161], v[182:185], v[112:115]
	v_mfma_f32_16x16x32_bf16 v[108:111], v[144:147], v[194:197], v[108:111]
	v_mfma_f32_16x16x32_bf16 v[100:103], v[158:161], v[194:197], v[100:103]
	v_mfma_f32_16x16x32_bf16 v[92:95], v[144:147], v[206:209], v[92:95]
	v_mfma_f32_16x16x32_bf16 v[84:87], v[158:161], v[206:209], v[84:87]
	v_mfma_f32_16x16x32_bf16 v[76:79], v[144:147], v[214:217], v[76:79]
	v_mfma_f32_16x16x32_bf16 v[68:71], v[158:161], v[214:217], v[68:71]
	s_setprio 0
	s_setprio 1
	v_mfma_f32_16x16x32_bf16 v[120:123], v[162:165], v[178:181], v[120:123]
	v_mfma_f32_16x16x32_bf16 v[116:119], v[170:173], v[178:181], v[116:119]
	v_mfma_f32_16x16x32_bf16 v[104:107], v[162:165], v[186:189], v[104:107]
	v_mfma_f32_16x16x32_bf16 v[96:99], v[170:173], v[186:189], v[96:99]
	v_mfma_f32_16x16x32_bf16 v[88:91], v[162:165], v[202:205], v[88:91]
	v_mfma_f32_16x16x32_bf16 v[80:83], v[170:173], v[202:205], v[80:83]
	v_mfma_f32_16x16x32_bf16 v[72:75], v[162:165], v[210:213], v[72:75]
	v_mfma_f32_16x16x32_bf16 v[64:67], v[170:173], v[210:213], v[64:67]
	v_mfma_f32_16x16x32_bf16 v[120:123], v[166:169], v[182:185], v[120:123]
	v_mfma_f32_16x16x32_bf16 v[116:119], v[174:177], v[182:185], v[116:119]
	v_mfma_f32_16x16x32_bf16 v[104:107], v[166:169], v[194:197], v[104:107]
	v_mfma_f32_16x16x32_bf16 v[96:99], v[174:177], v[194:197], v[96:99]
	v_mfma_f32_16x16x32_bf16 v[88:91], v[166:169], v[206:209], v[88:91]
	v_mfma_f32_16x16x32_bf16 v[80:83], v[174:177], v[206:209], v[80:83]
	v_mfma_f32_16x16x32_bf16 v[72:75], v[166:169], v[214:217], v[72:75]
	v_mfma_f32_16x16x32_bf16 v[64:67], v[174:177], v[214:217], v[64:67]
	s_setprio 0
	s_barrier
; #define PG8_STAGE(bufoff, gbase, voff) do { _Pragma("unroll") for (int _i = 0; _i < 2; ++_i) \
;         __builtin_amdgcn_global_load_lds((const unsigned*)((const char*)(gbase) + (voff)[_i]), (PG8_LAS unsigned*)(lds + (bufoff) + ldsw + _i * 8192), 16, 0, 0); } while (0)
; #define PG8_LDA(dst, b, h) do { _Pragma("unroll") for (int m = 0; m < 4; ++m) _Pragma("unroll") for (int k = 0; k < 2; ++k) dst[m][k] = *(const PG8_LAS bf16x8*)(lds + PG8_SA(b, h) + aoff + m * 2048 + k * 1024); } while (0)
; #define PG8_MMA(ai, bj, At, Bt) do { __builtin_amdgcn_s_setprio(1); _Pragma("unroll") for (int m = 0; m < 4; ++m) _Pragma("unroll") for (int n = 0; n < 2; ++n) _Pragma("unroll") for (int k = 0; k < 2; ++k) \
;         acc[ai][bj][m][n] = __builtin_amdgcn_mfma_f32_16x16x32_bf16(Bt[n][k], At[m][k], acc[ai][bj][m][n], 0, 0, 0); __builtin_amdgcn_s_setprio(0); } while (0)
; #define PG8_WAIT_V(n) asm volatile("s_waitcnt vmcnt(" #n ")" ::: "memory")
; #define PG8_WAIT_L(n) asm volatile("s_waitcnt lgkmcnt(" #n ")" ::: "memory")
; #define PG8_BAR __builtin_amdgcn_s_barrier()
; #define PG8_SCHED __builtin_amdgcn_sched_barrier(0)
; template <class Epi, class Sched, bool ALIGN_EPI = false, bool SP2 = false>
; __device__ __forceinline__ void gemm_phase(PG8_LAS unsigned char* lds, const Gemm g, const Sched& S, const Epi& E) {
;     ...
;             PG8_WAIT_V(8); PG8_WAIT_L(0); PG8_BAR; PG8_MMA(0, 0, At, B0); PG8_MMA(0, 1, At, B1); PG8_BAR; PG8_SCHED;
;             PG8_LDA(At, 1, 1); PG8_STAGE(PG8_SB(1, 0), b3, voffB); PG8_STAGE(PG8_SB(1, 1), b3 + hstep, voffB); PG8_STAGE(PG8_SA(1, 0), a3, voffA);
;             PG8_WAIT_V(8); PG8_WAIT_L(0); PG8_BAR; PG8_MMA(1, 0, At, B0); PG8_MMA(1, 1, At, B1); PG8_BAR; PG8_SCHED;
	s_add_i32 s12, s24, s30
	v_lshl_add_u64 v[190:191], v[190:191], 0, s[16:17]
	s_mov_b32 m0, s12
	ds_read_b128 v[178:181], v152 offset:49152
	ds_read_b128 v[182:185], v152 offset:50176
	ds_read_b128 v[186:189], v152 offset:51200
	ds_read_b128 v[194:197], v152 offset:52224
	ds_read_b128 v[202:205], v152 offset:53248
	ds_read_b128 v[206:209], v152 offset:54272
	ds_read_b128 v[210:213], v152 offset:55296
	ds_read_b128 v[214:217], v152 offset:56320
	global_load_lds_dwordx4 v[190:191], off
	s_add_i32 m0, s12, 0x2000
	s_add_u32 s10, s10, 0x80080
	v_lshl_add_u64 v[190:191], v[218:219], 0, s[16:17]
	s_addc_u32 s11, s11, 0
	s_add_i32 s12, s25, s30
	global_load_lds_dwordx4 v[190:191], off
	s_mov_b32 m0, s12
	v_lshl_add_u64 v[190:191], s[10:11], 0, v[132:133]
	global_load_lds_dwordx4 v[190:191], off
	s_add_i32 m0, s12, 0x2000
	v_lshl_add_u64 v[190:191], s[10:11], 0, v[128:129]
	global_load_lds_dwordx4 v[190:191], off
	s_mov_b32 m0, s56
	v_lshl_add_u64 v[190:191], v[220:221], 0, s[16:17]
	global_load_lds_dwordx4 v[190:191], off
	s_mov_b32 m0, s57
	v_lshl_add_u64 v[190:191], v[230:231], 0, s[16:17]
	global_load_lds_dwordx4 v[190:191], off
	s_waitcnt vmcnt(8)
	s_waitcnt lgkmcnt(0)
	s_barrier
	s_setprio 1
	s_waitcnt lgkmcnt(0)
	v_mfma_f32_16x16x32_bf16 v[60:63], v[140:143], v[178:181], v[60:63]
	v_mfma_f32_16x16x32_bf16 v[52:55], v[154:157], v[178:181], v[52:55]
	v_mfma_f32_16x16x32_bf16 v[44:47], v[140:143], v[186:189], v[44:47]
	v_mfma_f32_16x16x32_bf16 v[36:39], v[154:157], v[186:189], v[36:39]
	v_mfma_f32_16x16x32_bf16 v[28:31], v[140:143], v[202:205], v[28:31]
	v_mfma_f32_16x16x32_bf16 v[20:23], v[154:157], v[202:205], v[20:23]
	v_mfma_f32_16x16x32_bf16 v[12:15], v[140:143], v[210:213], v[12:15]
	v_mfma_f32_16x16x32_bf16 v[4:7], v[154:157], v[210:213], v[4:7]
	v_mfma_f32_16x16x32_bf16 v[60:63], v[144:147], v[182:185], v[60:63]
	v_mfma_f32_16x16x32_bf16 v[52:55], v[158:161], v[182:185], v[52:55]
	v_mfma_f32_16x16x32_bf16 v[44:47], v[144:147], v[194:197], v[44:47]
	v_mfma_f32_16x16x32_bf16 v[36:39], v[158:161], v[194:197], v[36:39]
	v_mfma_f32_16x16x32_bf16 v[28:31], v[144:147], v[206:209], v[28:31]
	v_mfma_f32_16x16x32_bf16 v[20:23], v[158:161], v[206:209], v[20:23]
	v_mfma_f32_16x16x32_bf16 v[12:15], v[144:147], v[214:217], v[12:15]
	v_mfma_f32_16x16x32_bf16 v[4:7], v[158:161], v[214:217], v[4:7]
	s_setprio 0
	s_setprio 1
	v_mfma_f32_16x16x32_bf16 v[56:59], v[162:165], v[178:181], v[56:59]
	v_mfma_f32_16x16x32_bf16 v[48:51], v[170:173], v[178:181], v[48:51]
	v_mfma_f32_16x16x32_bf16 v[40:43], v[162:165], v[186:189], v[40:43]
	v_mfma_f32_16x16x32_bf16 v[32:35], v[170:173], v[186:189], v[32:35]
	v_mfma_f32_16x16x32_bf16 v[24:27], v[162:165], v[202:205], v[24:27]
	v_mfma_f32_16x16x32_bf16 v[16:19], v[170:173], v[202:205], v[16:19]
	v_mfma_f32_16x16x32_bf16 v[8:11], v[162:165], v[210:213], v[8:11]
	v_mfma_f32_16x16x32_bf16 v[0:3], v[170:173], v[210:213], v[0:3]
	v_mfma_f32_16x16x32_bf16 v[56:59], v[166:169], v[182:185], v[56:59]
	v_mfma_f32_16x16x32_bf16 v[48:51], v[174:177], v[182:185], v[48:51]
	v_mfma_f32_16x16x32_bf16 v[40:43], v[166:169], v[194:197], v[40:43]
	v_mfma_f32_16x16x32_bf16 v[32:35], v[174:177], v[194:197], v[32:35]
	v_mfma_f32_16x16x32_bf16 v[24:27], v[166:169], v[206:209], v[24:27]
	v_mfma_f32_16x16x32_bf16 v[16:19], v[174:177], v[206:209], v[16:19]
	v_mfma_f32_16x16x32_bf16 v[8:11], v[166:169], v[214:217], v[8:11]
	v_mfma_f32_16x16x32_bf16 v[0:3], v[174:177], v[214:217], v[0:3]
	s_setprio 0
	s_barrier
	s_add_i32 s64, s64, 2
	s_add_u32 s0, s0, 0x100
	s_addc_u32 s1, s1, 0
	s_add_u32 s62, s62, 0x100
	s_addc_u32 s63, s63, 0
	s_cmp_gt_u32 s64, 29
	s_branch .LBB0_730

; #define PG8_STAGE(bufoff, gbase, voff) do { _Pragma("unroll") for (int _i = 0; _i < 2; ++_i) \
;         __builtin_amdgcn_global_load_lds((const unsigned*)((const char*)(gbase) + (voff)[_i]), (PG8_LAS unsigned*)(lds + (bufoff) + ldsw + _i * 8192), 16, 0, 0); } while (0)
; #define PG8_LDA(dst, b, h) do { _Pragma("unroll") for (int m = 0; m < 4; ++m) _Pragma("unroll") for (int k = 0; k < 2; ++k) dst[m][k] = *(const PG8_LAS bf16x8*)(lds + PG8_SA(b, h) + aoff + m * 2048 + k * 1024); } while (0)
; #define PG8_SCHED __builtin_amdgcn_sched_barrier(0)
;     __host__ __device__ bool next(int i, Unit& u) const {
;         int ii = i; if (rounds) { if (i >= rounds) return false; ii = i + rot; if (ii >= rounds) ii -= rounds; }
;         const long L = (long)ii * G + c; if (L >= nwg) return false;
;         int wgid = (int)L; { const int q = nwg / NXCD, r = nwg % NXCD, xcd = wgid % NXCD, off = wgid / NXCD; wgid = (xcd < r ? xcd * (q + 1) : r * (q + 1) + (xcd - r) * q) + off; }
;         const int nig = WGM * nN, gid = wgid / nig, fm = gid * WGM, gsz = (nM - fm) < WGM ? (nM - fm) : WGM;
;         u.pm = fm + ((wgid % nig) % gsz); u.pn = (wgid % nig) / gsz; return true;
; template <class Epi, class Sched, bool ALIGN_EPI = false, bool SP2 = false>
; __device__ __forceinline__ void gemm_phase(PG8_LAS unsigned char* lds, const Gemm g, const Sched& S, const Epi& E) {
;     ...
;         const bool has_next = S.next(ui + 1, nxt);
;         const char* nA = has_next ? (const char*)g.A + (size_t)nxt.pm * tstep : cA; const char* nB = has_next ? (const char*)g.Bt + (size_t)nxt.pn * tstep : cB;
;         for (int t = 0; t < nt; t += 2) {
;             if constexpr (Epi::MID_HOOK) { if (t == Epi::MID_T) E.mid(acc, cur, wr, wc, fr, fq); }
;             const bool last = (t == nt - 2);
;             const char* a1 = cA + (size_t)(t + 1) * kstep;
;             const char* a2 = last ? nA : cA + (size_t)(t + 2) * kstep; const char* b2 = last ? nB : cB + (size_t)(t + 2) * kstep;
;             const char* a3 = a2 + kstep; const char* b3 = b2 + kstep;
;             if (last && has_next) S.a_ready(nxt);
;             if constexpr (SP2) {
;             PG8_LDB(B0, 0, 0); PG8_LDB(B1, 0, 1); PG8_SCHED; PG8_LDA(At, 0, 0); PG8_STAGE(PG8_SA(1, 1), a1 + hstep, voffA);
.LBB0_806:
	v_add_u32_e32 v140, 0x10000, v172
	v_add_u32_e32 v168, 0x14000, v172
	ds_read_b128 v[128:131], v140
	ds_read_b128 v[132:135], v140 offset:1024
	ds_read_b128 v[136:139], v140 offset:2048
	ds_read_b128 v[140:143], v140 offset:3072
	ds_read_b128 v[144:147], v168
	ds_read_b128 v[148:151], v168 offset:1024
	ds_read_b128 v[164:167], v168 offset:2048
	ds_read_b128 v[174:177], v168 offset:3072
	ds_read_b128 v[178:181], v173
	ds_read_b128 v[182:185], v173 offset:1024
	ds_read_b128 v[186:189], v173 offset:2048
	ds_read_b128 v[194:197], v173 offset:3072
	ds_read_b128 v[202:205], v173 offset:4096
	ds_read_b128 v[206:209], v173 offset:5120
	ds_read_b128 v[210:213], v173 offset:6144
	ds_read_b128 v[214:217], v173 offset:7168
	s_add_i32 s54, s54, 1
	s_mul_i32 s0, s54, s53
	s_mul_hi_u32 s1, s54, s47
	s_add_i32 s1, s1, s0
	s_mul_i32 s0, s54, s47
	s_add_u32 s0, s0, s23
	v_readlane_b32 s4, v254, 44
	s_addc_u32 s1, s1, s4
	v_cmp_gt_i64_e32 vcc, s[0:1], v[200:201]
	v_cmp_lt_i64_e64 s[4:5], s[0:1], v[198:199]
	s_cbranch_vccnz .LBB0_812
	s_ashr_i32 s1, s0, 31
	s_lshr_b32 s1, s1, 29
	s_add_i32 s14, s0, s1
	s_and_b32 s1, s14, -8
	s_sub_i32 s15, s0, s1
	s_cmp_gt_i32 s15, -1
	s_mov_b64 s[0:1], -1
	s_cbranch_scc0 .LBB0_809
	s_lshl_b32 s36, s15, 6
	s_mov_b64 s[0:1], 0

; #define PG8_STAGE(bufoff, gbase, voff) do { _Pragma("unroll") for (int _i = 0; _i < 2; ++_i) \
;         __builtin_amdgcn_global_load_lds((const unsigned*)((const char*)(gbase) + (voff)[_i]), (PG8_LAS unsigned*)(lds + (bufoff) + ldsw + _i * 8192), 16, 0, 0); } while (0)
; #define PG8_LDA(dst, b, h) do { _Pragma("unroll") for (int m = 0; m < 4; ++m) _Pragma("unroll") for (int k = 0; k < 2; ++k) dst[m][k] = *(const PG8_LAS bf16x8*)(lds + PG8_SA(b, h) + aoff + m * 2048 + k * 1024); } while (0)
; #define PG8_LDB(dst, b, h) do { _Pragma("unroll") for (int n = 0; n < 2; ++n) _Pragma("unroll") for (int k = 0; k < 2; ++k) dst[n][k] = *(const PG8_LAS bf16x8*)(lds + PG8_SB(b, h) + boff + n * 2048 + k * 1024); } while (0)
; #define PG8_MMA(ai, bj, At, Bt) do { __builtin_amdgcn_s_setprio(1); _Pragma("unroll") for (int m = 0; m < 4; ++m) _Pragma("unroll") for (int n = 0; n < 2; ++n) _Pragma("unroll") for (int k = 0; k < 2; ++k) \
;         acc[ai][bj][m][n] = __builtin_amdgcn_mfma_f32_16x16x32_bf16(Bt[n][k], At[m][k], acc[ai][bj][m][n], 0, 0, 0); __builtin_amdgcn_s_setprio(0); } while (0)
; #define PG8_WAIT_V(n) asm volatile("s_waitcnt vmcnt(" #n ")" ::: "memory")
; #define PG8_WAIT_L(n) asm volatile("s_waitcnt lgkmcnt(" #n ")" ::: "memory")
; template <class Epi, class Sched, bool ALIGN_EPI = false, bool SP2 = false>
; __device__ __forceinline__ void gemm_phase(PG8_LAS unsigned char* lds, const Gemm g, const Sched& S, const Epi& E) {
;     ...
;             const bool last = (t == nt - 2);
;             const char* a1 = cA + (size_t)(t + 1) * kstep;
;             const char* a2 = last ? nA : cA + (size_t)(t + 2) * kstep; const char* b2 = last ? nB : cB + (size_t)(t + 2) * kstep;
;             const char* a3 = a2 + kstep; const char* b3 = b2 + kstep;
;             if (last && has_next) S.a_ready(nxt);
;             if constexpr (SP2) {
;             PG8_LDB(B0, 0, 0); PG8_LDB(B1, 0, 1); PG8_SCHED; PG8_LDA(At, 0, 0); PG8_STAGE(PG8_SA(1, 1), a1 + hstep, voffA);
;             PG8_WAIT_V(8); PG8_WAIT_L(0); PG8_BAR; PG8_MMA(0, 0, At, B0); PG8_MMA(0, 1, At, B1); PG8_BAR; PG8_SCHED;
;             PG8_LDA(At, 0, 1); PG8_STAGE(PG8_SB(0, 0), b2, voffB); PG8_STAGE(PG8_SB(0, 1), b2 + hstep, voffB); PG8_STAGE(PG8_SA(0, 0), a2, voffA);
;             PG8_WAIT_V(8); PG8_WAIT_L(0); PG8_BAR; PG8_MMA(1, 0, At, B0); PG8_MMA(1, 1, At, B1); PG8_BAR; PG8_SCHED;
.LBB0_816:
	s_add_u32 s59, s30, 0x100
	s_addc_u32 s60, s31, 0
	s_mov_b32 s61, -2
	s_waitcnt lgkmcnt(0)
	v_lshl_add_u64 v[168:169], s[18:19], 0, v[160:161]
	s_add_i32 m0, s2, 0xc000
	global_load_lds_dwordx4 v[168:169], off
	s_add_i32 m0, s2, 0xe000
	v_lshl_add_u64 v[168:169], s[18:19], 0, v[162:163]
	global_load_lds_dwordx4 v[168:169], off
	s_add_u32 s30, s18, 0x100
	s_addc_u32 s31, s19, 0
	s_add_i32 s24, 0, 0x10000
	s_cmpk_eq_i32 s61, 0x54
	s_cselect_b32 s39, s5, s31
	s_cselect_b32 s38, s4, s30
	s_cselect_b32 s37, s15, s60
	s_cselect_b32 s36, s14, s59
	s_add_i32 s25, 0, 0x14000
	s_waitcnt vmcnt(8)
	s_waitcnt lgkmcnt(0)
	s_barrier
	s_setprio 1
	s_waitcnt lgkmcnt(0)
	v_mfma_f32_16x16x32_bf16 v[124:127], v[128:131], v[178:181], 0
	v_mfma_f32_16x16x32_bf16 v[120:123], v[136:139], v[178:181], 0
	v_mfma_f32_16x16x32_bf16 v[108:111], v[128:131], v[186:189], 0
	v_mfma_f32_16x16x32_bf16 v[104:107], v[136:139], v[186:189], 0
	v_mfma_f32_16x16x32_bf16 v[92:95], v[128:131], v[202:205], 0
	v_mfma_f32_16x16x32_bf16 v[88:91], v[136:139], v[202:205], 0
	v_mfma_f32_16x16x32_bf16 v[76:79], v[128:131], v[210:213], 0
	v_mfma_f32_16x16x32_bf16 v[72:75], v[136:139], v[210:213], 0
	v_mfma_f32_16x16x32_bf16 v[124:127], v[132:135], v[182:185], v[124:127]
	v_mfma_f32_16x16x32_bf16 v[120:123], v[140:143], v[182:185], v[120:123]
	v_mfma_f32_16x16x32_bf16 v[108:111], v[132:135], v[194:197], v[108:111]
	v_mfma_f32_16x16x32_bf16 v[104:107], v[140:143], v[194:197], v[104:107]
	v_mfma_f32_16x16x32_bf16 v[92:95], v[132:135], v[206:209], v[92:95]
	v_mfma_f32_16x16x32_bf16 v[88:91], v[140:143], v[206:209], v[88:91]
	v_mfma_f32_16x16x32_bf16 v[76:79], v[132:135], v[214:217], v[76:79]
	v_mfma_f32_16x16x32_bf16 v[72:75], v[140:143], v[214:217], v[72:75]
	s_setprio 0
	s_setprio 1
	v_mfma_f32_16x16x32_bf16 v[116:119], v[144:147], v[178:181], 0
	v_mfma_f32_16x16x32_bf16 v[112:115], v[164:167], v[178:181], 0
	v_mfma_f32_16x16x32_bf16 v[100:103], v[144:147], v[186:189], 0
	v_mfma_f32_16x16x32_bf16 v[96:99], v[164:167], v[186:189], 0
	v_mfma_f32_16x16x32_bf16 v[84:87], v[144:147], v[202:205], 0
	v_mfma_f32_16x16x32_bf16 v[80:83], v[164:167], v[202:205], 0
	v_mfma_f32_16x16x32_bf16 v[68:71], v[144:147], v[210:213], 0
	v_mfma_f32_16x16x32_bf16 v[64:67], v[164:167], v[210:213], 0
	v_mfma_f32_16x16x32_bf16 v[116:119], v[148:151], v[182:185], v[116:119]
	v_mfma_f32_16x16x32_bf16 v[112:115], v[174:177], v[182:185], v[112:115]
	v_mfma_f32_16x16x32_bf16 v[100:103], v[148:151], v[194:197], v[100:103]
	v_mfma_f32_16x16x32_bf16 v[96:99], v[174:177], v[194:197], v[96:99]
	v_mfma_f32_16x16x32_bf16 v[84:87], v[148:151], v[206:209], v[84:87]
	v_mfma_f32_16x16x32_bf16 v[80:83], v[174:177], v[206:209], v[80:83]
	v_mfma_f32_16x16x32_bf16 v[68:71], v[148:151], v[214:217], v[68:71]
	v_mfma_f32_16x16x32_bf16 v[64:67], v[174:177], v[214:217], v[64:67]
	s_setprio 0
	s_barrier
	s_add_i32 s18, s24, s43
	v_lshl_add_u64 v[168:169], s[36:37], 0, v[156:157]
	s_mov_b32 m0, s18
	ds_read_b128 v[178:181], v173 offset:16384
	ds_read_b128 v[182:185], v173 offset:17408
	ds_read_b128 v[186:189], v173 offset:18432
	ds_read_b128 v[194:197], v173 offset:19456
	ds_read_b128 v[202:205], v173 offset:20480
	ds_read_b128 v[206:209], v173 offset:21504
	ds_read_b128 v[210:213], v173 offset:22528
	ds_read_b128 v[214:217], v173 offset:23552
	global_load_lds_dwordx4 v[168:169], off
	s_add_i32 m0, s18, 0x2000
	s_add_u32 s18, s36, 0x160000
	v_lshl_add_u64 v[190:191], s[36:37], 0, v[152:153]
	s_addc_u32 s19, s37, 0
	s_add_i32 s24, s25, s43
	global_load_lds_dwordx4 v[190:191], off
	v_lshl_add_u64 v[218:219], s[18:19], 0, v[156:157]
	s_mov_b32 m0, s24
	v_lshl_add_u64 v[220:221], s[38:39], 0, v[154:155]
	global_load_lds_dwordx4 v[218:219], off
	s_add_i32 m0, s24, 0x2000
	v_lshl_add_u64 v[218:219], s[18:19], 0, v[152:153]
	global_load_lds_dwordx4 v[218:219], off
	s_mov_b32 m0, s2
	v_lshl_add_u64 v[218:219], s[38:39], 0, v[158:159]
	global_load_lds_dwordx4 v[218:219], off
	s_mov_b32 m0, s44
	s_nop 0
	global_load_lds_dwordx4 v[220:221], off
	s_waitcnt vmcnt(8)
	s_waitcnt lgkmcnt(0)
	s_barrier
	s_setprio 1
	s_waitcnt lgkmcnt(0)
	v_mfma_f32_16x16x32_bf16 v[60:63], v[128:131], v[178:181], 0
	v_mfma_f32_16x16x32_bf16 v[56:59], v[136:139], v[178:181], 0
	v_mfma_f32_16x16x32_bf16 v[44:47], v[128:131], v[186:189], 0
	v_mfma_f32_16x16x32_bf16 v[40:43], v[136:139], v[186:189], 0
	v_mfma_f32_16x16x32_bf16 v[28:31], v[128:131], v[202:205], 0
	v_mfma_f32_16x16x32_bf16 v[24:27], v[136:139], v[202:205], 0
	v_mfma_f32_16x16x32_bf16 v[12:15], v[128:131], v[210:213], 0
	v_mfma_f32_16x16x32_bf16 v[8:11], v[136:139], v[210:213], 0
	v_mfma_f32_16x16x32_bf16 v[60:63], v[132:135], v[182:185], v[60:63]
	v_mfma_f32_16x16x32_bf16 v[56:59], v[140:143], v[182:185], v[56:59]
	v_mfma_f32_16x16x32_bf16 v[44:47], v[132:135], v[194:197], v[44:47]
	v_mfma_f32_16x16x32_bf16 v[40:43], v[140:143], v[194:197], v[40:43]
	v_mfma_f32_16x16x32_bf16 v[28:31], v[132:135], v[206:209], v[28:31]
	v_mfma_f32_16x16x32_bf16 v[24:27], v[140:143], v[206:209], v[24:27]
	v_mfma_f32_16x16x32_bf16 v[12:15], v[132:135], v[214:217], v[12:15]
	v_mfma_f32_16x16x32_bf16 v[8:11], v[140:143], v[214:217], v[8:11]
	s_setprio 0
	s_setprio 1
	v_mfma_f32_16x16x32_bf16 v[52:55], v[144:147], v[178:181], 0
	v_mfma_f32_16x16x32_bf16 v[48:51], v[164:167], v[178:181], 0
	v_mfma_f32_16x16x32_bf16 v[36:39], v[144:147], v[186:189], 0
	v_mfma_f32_16x16x32_bf16 v[32:35], v[164:167], v[186:189], 0
	v_mfma_f32_16x16x32_bf16 v[20:23], v[144:147], v[202:205], 0
	v_mfma_f32_16x16x32_bf16 v[16:19], v[164:167], v[202:205], 0
	v_mfma_f32_16x16x32_bf16 v[4:7], v[144:147], v[210:213], 0
	v_mfma_f32_16x16x32_bf16 v[0:3], v[164:167], v[210:213], 0
	v_mfma_f32_16x16x32_bf16 v[52:55], v[148:151], v[182:185], v[52:55]
	v_mfma_f32_16x16x32_bf16 v[48:51], v[174:177], v[182:185], v[48:51]
	v_mfma_f32_16x16x32_bf16 v[36:39], v[148:151], v[194:197], v[36:39]
	v_mfma_f32_16x16x32_bf16 v[32:35], v[174:177], v[194:197], v[32:35]
	v_mfma_f32_16x16x32_bf16 v[20:23], v[148:151], v[206:209], v[20:23]
	v_mfma_f32_16x16x32_bf16 v[16:19], v[174:177], v[206:209], v[16:19]
	v_mfma_f32_16x16x32_bf16 v[4:7], v[148:151], v[214:217], v[4:7]
	v_mfma_f32_16x16x32_bf16 v[0:3], v[174:177], v[214:217], v[0:3]
	s_setprio 0
	s_barrier
; #define PG8_STAGE(bufoff, gbase, voff) do { _Pragma("unroll") for (int _i = 0; _i < 2; ++_i) \
;         __builtin_amdgcn_global_load_lds((const unsigned*)((const char*)(gbase) + (voff)[_i]), (PG8_LAS unsigned*)(lds + (bufoff) + ldsw + _i * 8192), 16, 0, 0); } while (0)
; #define PG8_LDA(dst, b, h) do { _Pragma("unroll") for (int m = 0; m < 4; ++m) _Pragma("unroll") for (int k = 0; k < 2; ++k) dst[m][k] = *(const PG8_LAS bf16x8*)(lds + PG8_SA(b, h) + aoff + m * 2048 + k * 1024); } while (0)
; #define PG8_LDB(dst, b, h) do { _Pragma("unroll") for (int n = 0; n < 2; ++n) _Pragma("unroll") for (int k = 0; k < 2; ++k) dst[n][k] = *(const PG8_LAS bf16x8*)(lds + PG8_SB(b, h) + boff + n * 2048 + k * 1024); } while (0)
; #define PG8_MMA(ai, bj, At, Bt) do { __builtin_amdgcn_s_setprio(1); _Pragma("unroll") for (int m = 0; m < 4; ++m) _Pragma("unroll") for (int n = 0; n < 2; ++n) _Pragma("unroll") for (int k = 0; k < 2; ++k) \
;         acc[ai][bj][m][n] = __builtin_amdgcn_mfma_f32_16x16x32_bf16(Bt[n][k], At[m][k], acc[ai][bj][m][n], 0, 0, 0); __builtin_amdgcn_s_setprio(0); } while (0)
; #define PG8_WAIT_V(n) asm volatile("s_waitcnt vmcnt(" #n ")" ::: "memory")
; #define PG8_WAIT_L(n) asm volatile("s_waitcnt lgkmcnt(" #n ")" ::: "memory")
; #define PG8_BAR __builtin_amdgcn_s_barrier()
; #define PG8_SCHED __builtin_amdgcn_sched_barrier(0)
; template <class Epi, class Sched, bool ALIGN_EPI = false, bool SP2 = false>
; __device__ __forceinline__ void gemm_phase(PG8_LAS unsigned char* lds, const Gemm g, const Sched& S, const Epi& E) {
;     ...
;             PG8_LDB(B0, 1, 0); PG8_LDB(B1, 1, 1); PG8_SCHED; PG8_LDA(At, 1, 0); PG8_STAGE(PG8_SA(0, 1), a2 + hstep, voffA);
;             PG8_WAIT_V(8); PG8_WAIT_L(0); PG8_BAR; PG8_MMA(0, 0, At, B0); PG8_MMA(0, 1, At, B1); PG8_BAR; PG8_SCHED;
;             PG8_LDA(At, 1, 1); PG8_STAGE(PG8_SB(1, 0), b3, voffB); PG8_STAGE(PG8_SB(1, 1), b3 + hstep, voffB); PG8_STAGE(PG8_SA(1, 0), a3, voffA);
;             PG8_WAIT_V(8); PG8_WAIT_L(0); PG8_BAR; PG8_MMA(1, 0, At, B0); PG8_MMA(1, 1, At, B1); PG8_BAR; PG8_SCHED;
	s_add_i32 s24, 0, 0x18000
	s_add_i32 s25, 0, 0x1c000
	v_add_u32_e32 v140, 0x18000, v172
	v_add_u32_e32 v174, 0x1c000, v172
	ds_read_b128 v[128:131], v140
	ds_read_b128 v[132:135], v140 offset:1024
	ds_read_b128 v[136:139], v140 offset:2048
	ds_read_b128 v[140:143], v140 offset:3072
	ds_read_b128 v[144:147], v174
	ds_read_b128 v[148:151], v174 offset:1024
	ds_read_b128 v[164:167], v174 offset:2048
	ds_read_b128 v[174:177], v174 offset:3072
	s_add_u32 s18, s38, 0x160000
	s_addc_u32 s19, s39, 0
	s_mov_b32 m0, s45
	v_lshl_add_u64 v[230:231], s[18:19], 0, v[158:159]
	ds_read_b128 v[178:181], v173 offset:32768
	ds_read_b128 v[182:185], v173 offset:33792
	ds_read_b128 v[186:189], v173 offset:34816
	ds_read_b128 v[194:197], v173 offset:35840
	ds_read_b128 v[202:205], v173 offset:36864
	ds_read_b128 v[206:209], v173 offset:37888
	ds_read_b128 v[210:213], v173 offset:38912
	ds_read_b128 v[214:217], v173 offset:39936
	global_load_lds_dwordx4 v[230:231], off
	s_mov_b32 m0, s46
	v_lshl_add_u64 v[230:231], s[18:19], 0, v[154:155]
	global_load_lds_dwordx4 v[230:231], off
	s_waitcnt vmcnt(8)
	s_waitcnt lgkmcnt(0)
	s_barrier
	s_setprio 1
	s_waitcnt lgkmcnt(0)
	v_mfma_f32_16x16x32_bf16 v[124:127], v[128:131], v[178:181], v[124:127]
	v_mfma_f32_16x16x32_bf16 v[120:123], v[136:139], v[178:181], v[120:123]
	v_mfma_f32_16x16x32_bf16 v[108:111], v[128:131], v[186:189], v[108:111]
	v_mfma_f32_16x16x32_bf16 v[104:107], v[136:139], v[186:189], v[104:107]
	v_mfma_f32_16x16x32_bf16 v[92:95], v[128:131], v[202:205], v[92:95]
	v_mfma_f32_16x16x32_bf16 v[88:91], v[136:139], v[202:205], v[88:91]
	v_mfma_f32_16x16x32_bf16 v[76:79], v[128:131], v[210:213], v[76:79]
	v_mfma_f32_16x16x32_bf16 v[72:75], v[136:139], v[210:213], v[72:75]
	v_mfma_f32_16x16x32_bf16 v[124:127], v[132:135], v[182:185], v[124:127]
	v_mfma_f32_16x16x32_bf16 v[120:123], v[140:143], v[182:185], v[120:123]
	v_mfma_f32_16x16x32_bf16 v[108:111], v[132:135], v[194:197], v[108:111]
	v_mfma_f32_16x16x32_bf16 v[104:107], v[140:143], v[194:197], v[104:107]
	v_mfma_f32_16x16x32_bf16 v[92:95], v[132:135], v[206:209], v[92:95]
	v_mfma_f32_16x16x32_bf16 v[88:91], v[140:143], v[206:209], v[88:91]
	v_mfma_f32_16x16x32_bf16 v[76:79], v[132:135], v[214:217], v[76:79]
	v_mfma_f32_16x16x32_bf16 v[72:75], v[140:143], v[214:217], v[72:75]
	s_setprio 0
	s_setprio 1
	v_mfma_f32_16x16x32_bf16 v[116:119], v[144:147], v[178:181], v[116:119]
	v_mfma_f32_16x16x32_bf16 v[112:115], v[164:167], v[178:181], v[112:115]
	v_mfma_f32_16x16x32_bf16 v[100:103], v[144:147], v[186:189], v[100:103]
	v_mfma_f32_16x16x32_bf16 v[96:99], v[164:167], v[186:189], v[96:99]
	v_mfma_f32_16x16x32_bf16 v[84:87], v[144:147], v[202:205], v[84:87]
	v_mfma_f32_16x16x32_bf16 v[80:83], v[164:167], v[202:205], v[80:83]
	v_mfma_f32_16x16x32_bf16 v[68:71], v[144:147], v[210:213], v[68:71]
	v_mfma_f32_16x16x32_bf16 v[64:67], v[164:167], v[210:213], v[64:67]
	v_mfma_f32_16x16x32_bf16 v[116:119], v[148:151], v[182:185], v[116:119]
	v_mfma_f32_16x16x32_bf16 v[112:115], v[174:177], v[182:185], v[112:115]
	v_mfma_f32_16x16x32_bf16 v[100:103], v[148:151], v[194:197], v[100:103]
	v_mfma_f32_16x16x32_bf16 v[96:99], v[174:177], v[194:197], v[96:99]
	v_mfma_f32_16x16x32_bf16 v[84:87], v[148:151], v[206:209], v[84:87]
	v_mfma_f32_16x16x32_bf16 v[80:83], v[174:177], v[206:209], v[80:83]
	v_mfma_f32_16x16x32_bf16 v[68:71], v[148:151], v[214:217], v[68:71]
	v_mfma_f32_16x16x32_bf16 v[64:67], v[174:177], v[214:217], v[64:67]
	s_setprio 0
	s_barrier
; #define PG8_STAGE(bufoff, gbase, voff) do { _Pragma("unroll") for (int _i = 0; _i < 2; ++_i) \
;         __builtin_amdgcn_global_load_lds((const unsigned*)((const char*)(gbase) + (voff)[_i]), (PG8_LAS unsigned*)(lds + (bufoff) + ldsw + _i * 8192), 16, 0, 0); } while (0)
; #define PG8_LDA(dst, b, h) do { _Pragma("unroll") for (int m = 0; m < 4; ++m) _Pragma("unroll") for (int k = 0; k < 2; ++k) dst[m][k] = *(const PG8_LAS bf16x8*)(lds + PG8_SA(b, h) + aoff + m * 2048 + k * 1024); } while (0)
; #define PG8_MMA(ai, bj, At, Bt) do { __builtin_amdgcn_s_setprio(1); _Pragma("unroll") for (int m = 0; m < 4; ++m) _Pragma("unroll") for (int n = 0; n < 2; ++n) _Pragma("unroll") for (int k = 0; k < 2; ++k) \
;         acc[ai][bj][m][n] = __builtin_amdgcn_mfma_f32_16x16x32_bf16(Bt[n][k], At[m][k], acc[ai][bj][m][n], 0, 0, 0); __builtin_amdgcn_s_setprio(0); } while (0)
; #define PG8_WAIT_V(n) asm volatile("s_waitcnt vmcnt(" #n ")" ::: "memory")
; #define PG8_WAIT_L(n) asm volatile("s_waitcnt lgkmcnt(" #n ")" ::: "memory")
; #define PG8_BAR __builtin_amdgcn_s_barrier()
; #define PG8_SCHED __builtin_amdgcn_sched_barrier(0)
; template <class Epi, class Sched, bool ALIGN_EPI = false, bool SP2 = false>
; __device__ __forceinline__ void gemm_phase(PG8_LAS unsigned char* lds, const Gemm g, const Sched& S, const Epi& E) {
;     ...
;             PG8_WAIT_V(8); PG8_WAIT_L(0); PG8_BAR; PG8_MMA(0, 0, At, B0); PG8_MMA(0, 1, At, B1); PG8_BAR; PG8_SCHED;
;             PG8_LDA(At, 1, 1); PG8_STAGE(PG8_SB(1, 0), b3, voffB); PG8_STAGE(PG8_SB(1, 1), b3 + hstep, voffB); PG8_STAGE(PG8_SA(1, 0), a3, voffA);
;             PG8_WAIT_V(8); PG8_WAIT_L(0); PG8_BAR; PG8_MMA(1, 0, At, B0); PG8_MMA(1, 1, At, B1); PG8_BAR; PG8_SCHED;
	s_add_i32 s18, s24, s43
	v_lshl_add_u64 v[168:169], v[168:169], 0, s[16:17]
	s_mov_b32 m0, s18
	ds_read_b128 v[178:181], v173 offset:49152
	ds_read_b128 v[182:185], v173 offset:50176
	ds_read_b128 v[186:189], v173 offset:51200
	ds_read_b128 v[194:197], v173 offset:52224
	ds_read_b128 v[202:205], v173 offset:53248
	ds_read_b128 v[206:209], v173 offset:54272
	ds_read_b128 v[210:213], v173 offset:55296
	ds_read_b128 v[214:217], v173 offset:56320
	global_load_lds_dwordx4 v[168:169], off
	s_add_i32 m0, s18, 0x2000
	s_add_u32 s18, s36, 0x160080
	v_lshl_add_u64 v[168:169], v[190:191], 0, s[16:17]
	s_addc_u32 s19, s37, 0
	s_add_i32 s24, s25, s43
	global_load_lds_dwordx4 v[168:169], off
	s_mov_b32 m0, s24
	v_lshl_add_u64 v[168:169], s[18:19], 0, v[156:157]
	global_load_lds_dwordx4 v[168:169], off
	s_add_i32 m0, s24, 0x2000
	v_lshl_add_u64 v[168:169], s[18:19], 0, v[152:153]
	global_load_lds_dwordx4 v[168:169], off
	s_mov_b32 m0, s51
	v_lshl_add_u64 v[168:169], v[218:219], 0, s[16:17]
	global_load_lds_dwordx4 v[168:169], off
	s_mov_b32 m0, s52
	v_lshl_add_u64 v[168:169], v[220:221], 0, s[16:17]
	global_load_lds_dwordx4 v[168:169], off
	s_waitcnt vmcnt(8)
	s_waitcnt lgkmcnt(0)
	s_barrier
	s_setprio 1
	s_waitcnt lgkmcnt(0)
	v_mfma_f32_16x16x32_bf16 v[60:63], v[128:131], v[178:181], v[60:63]
	v_mfma_f32_16x16x32_bf16 v[56:59], v[136:139], v[178:181], v[56:59]
	v_mfma_f32_16x16x32_bf16 v[44:47], v[128:131], v[186:189], v[44:47]
	v_mfma_f32_16x16x32_bf16 v[40:43], v[136:139], v[186:189], v[40:43]
	v_mfma_f32_16x16x32_bf16 v[28:31], v[128:131], v[202:205], v[28:31]
	v_mfma_f32_16x16x32_bf16 v[24:27], v[136:139], v[202:205], v[24:27]
	v_mfma_f32_16x16x32_bf16 v[12:15], v[128:131], v[210:213], v[12:15]
	v_mfma_f32_16x16x32_bf16 v[8:11], v[136:139], v[210:213], v[8:11]
	v_mfma_f32_16x16x32_bf16 v[60:63], v[132:135], v[182:185], v[60:63]
	v_mfma_f32_16x16x32_bf16 v[56:59], v[140:143], v[182:185], v[56:59]
	v_mfma_f32_16x16x32_bf16 v[44:47], v[132:135], v[194:197], v[44:47]
	v_mfma_f32_16x16x32_bf16 v[40:43], v[140:143], v[194:197], v[40:43]
	v_mfma_f32_16x16x32_bf16 v[28:31], v[132:135], v[206:209], v[28:31]
	v_mfma_f32_16x16x32_bf16 v[24:27], v[140:143], v[206:209], v[24:27]
	v_mfma_f32_16x16x32_bf16 v[12:15], v[132:135], v[214:217], v[12:15]
	v_mfma_f32_16x16x32_bf16 v[8:11], v[140:143], v[214:217], v[8:11]
	s_setprio 0
	s_setprio 1
	v_mfma_f32_16x16x32_bf16 v[52:55], v[144:147], v[178:181], v[52:55]
	v_mfma_f32_16x16x32_bf16 v[48:51], v[164:167], v[178:181], v[48:51]
	v_mfma_f32_16x16x32_bf16 v[36:39], v[144:147], v[186:189], v[36:39]
	v_mfma_f32_16x16x32_bf16 v[32:35], v[164:167], v[186:189], v[32:35]
	v_mfma_f32_16x16x32_bf16 v[20:23], v[144:147], v[202:205], v[20:23]
	v_mfma_f32_16x16x32_bf16 v[16:19], v[164:167], v[202:205], v[16:19]
	v_mfma_f32_16x16x32_bf16 v[4:7], v[144:147], v[210:213], v[4:7]
	v_mfma_f32_16x16x32_bf16 v[0:3], v[164:167], v[210:213], v[0:3]
	v_mfma_f32_16x16x32_bf16 v[52:55], v[148:151], v[182:185], v[52:55]
	v_mfma_f32_16x16x32_bf16 v[48:51], v[174:177], v[182:185], v[48:51]
	v_mfma_f32_16x16x32_bf16 v[36:39], v[148:151], v[194:197], v[36:39]
	v_mfma_f32_16x16x32_bf16 v[32:35], v[174:177], v[194:197], v[32:35]
	v_mfma_f32_16x16x32_bf16 v[20:23], v[148:151], v[206:209], v[20:23]
	v_mfma_f32_16x16x32_bf16 v[16:19], v[174:177], v[206:209], v[16:19]
	v_mfma_f32_16x16x32_bf16 v[4:7], v[148:151], v[214:217], v[4:7]
	v_mfma_f32_16x16x32_bf16 v[0:3], v[174:177], v[214:217], v[0:3]
	s_setprio 0
	s_barrier
	s_add_i32 s61, s61, 2
	s_add_u32 s59, s59, 0x100
	s_addc_u32 s60, s60, 0
	s_cmpk_gt_u32 s61, 0x55
	s_mov_b64 s[18:19], s[30:31]
	s_branch .LBB0_817
